# A loop: V^T fragments read once per tile and shared by both sub-heads; EpiBranch ratio vmcnt ladder; store drains off critical path in P3 elem loop and MLA task
# speedup vs baseline: 1.0520x; 1.0119x over previous
; #define PH(k) _Pragma("unroll 1") for (int rep_ = 0; rep_ < (int)(((PH_MASK >> (k)) & 1) + ((DUP_MASK >> (k)) & 1)); ++rep_)
; #define TIDS() const int tid = otid(), lane = tid & 63, wave = __builtin_amdgcn_readfirstlane(tid >> 6), gw = vcu * NWAVES + wave, gtid = vcu * NTHR + tid; (void)lane; (void)gw; (void)gtid
; #define WSP(name) unsigned char* name = a.ws; asm volatile("" : "+s"(name))
; template <int NTK>
; __device__ __forceinline__ void pp_elem(const int (&toks)[NTK], bf16_t* PROJ, bf16_t* KC, const float2* rope, const float* dqn, const float* dkn, int lane) {
;     int e0, c, sec = 0; bool isD = false; float sc = 1.f; const float* gn = dqn;
;     if (lane < 32) { sec = lane >> 1; c = lane & 1; e0 = PA + sec * 32 + c * 8; }
;     else if (lane < 56) { const int t = lane - 32, hd = t >> 2; sec = (t >> 1) & 1; c = t & 1; e0 = PD + hd * 64 + sec * 32 + c * 8; isD = true; gn = ((hd < 4) ? dqn : dkn) + sec * 32 + c * 8; sc = (hd < 4) ? 0.125f * LOG2E : 1.f; }
;     else { c = lane & 1; e0 = PC + 320 + c * 8; }
;     const bool active = lane < 58, isC = lane >= 56;
; __global__ void __launch_bounds__(NTHR, 2) mega_fwd(Args a) {
;     ...
;             PH(3) { WSP(w); TIDS(); bf16_t* PROJ = (bf16_t*)(w + WS_PROJ);
;                 bf16_t* KC = (bf16_t*)(w + WS_KC); const float2* rope = (const float2*)(w + WS_ROPE);
; #pragma unroll 1
;                 for (int t0 = gw; t0 < T; t0 += 2 * NGW) { if (t0 + NGW < T) { const int tk[2] = {t0, t0 + NGW}; pp_elem<2>(tk, PROJ, KC, rope, a.in[14] + l * 64, a.in[15] + l * 64, lane); }
;                                                           else { const int tk[1] = {t0}; pp_elem<1>(tk, PROJ, KC, rope, a.in[14] + l * 64, a.in[15] + l * 64, lane); } }
.LBB0_402:
	s_or_b64 exec, exec, s[4:5]
	s_xor_b64 s[4:5], s[36:37], -1
	v_writelane_b32 v254, s4, 63
	s_waitcnt lgkmcnt(0)
	v_mov_b32_e32 v0, v240
	v_writelane_b32 v255, s5, 0
	s_mov_b64 s[4:5], s[86:87]
	s_barrier
	s_lshl_b32 s12, s62, 6
	v_readfirstlane_b32 s6, v0
	s_ashr_i32 s8, s6, 6
	s_add_i32 s16, s8, s97
	s_cmp_lt_i32 s16, s0
	s_mov_b32 s13, s17
	s_cbranch_scc0 .LBB0_442
	v_readlane_b32 s68, v253, 16
	s_lshl_b64 s[10:11], s[12:13], 2
	v_readlane_b32 s80, v253, 28
	v_and_b32_e32 v1, 63, v0
	v_readlane_b32 s81, v253, 29
	s_add_u32 s6, s80, s10
	v_subrev_co_u32_e32 v2, vcc, 32, v1
	v_lshlrev_b32_e32 v3, 3, v0
	v_readlane_b32 s82, v253, 30
	s_addc_u32 s7, s81, s11
	v_and_b32_e32 v4, 8, v3
	v_bfe_u32 v7, v0, 1, 1
	v_lshlrev_b32_e32 v3, 4, v2
	v_readlane_b32 s83, v253, 31
	s_add_u32 s9, s82, s10
	v_and_b32_e32 v3, 0x7fffffc0, v3
	v_lshlrev_b32_e32 v8, 5, v7
	s_addc_u32 s14, s83, s11
	v_or3_b32 v3, v3, v8, v4
	s_xor_b64 s[10:11], vcc, -1
	v_add_u32_e32 v8, 0x600, v3
	v_mov_b32_e32 v3, s14
	v_mov_b32_e32 v9, s7
	v_cmp_gt_u32_e32 vcc, 16, v2
	v_mov_b32_e32 v2, s9
	v_mov_b32_e32 v10, s6
	v_cndmask_b32_e32 v3, v3, v9, vcc
	v_cndmask_b32_e32 v2, v2, v10, vcc
	v_lshlrev_b32_e32 v192, 7, v7
	v_lshl_add_u64 v[2:3], v[2:3], 0, v[192:193]
	v_lshlrev_b32_e32 v192, 2, v4
	v_lshl_add_u64 v[2:3], v[2:3], 0, v[192:193]
	v_cmp_gt_u32_e64 s[42:43], 56, v1
	v_lshlrev_b32_e32 v192, 3, v4
	v_readlane_b32 s9, v254, 28
	v_lshrrev_b32_e32 v6, 1, v0
	v_bfe_u32 v86, v0, 1, 5
	v_cmp_gt_u32_e64 s[38:39], 58, v1
	v_cmp_lt_u32_e64 s[40:41], 57, v1
	v_cndmask_b32_e64 v65, v9, v3, s[42:43]
	v_cndmask_b32_e64 v64, v10, v2, s[42:43]
	v_and_b32_e32 v1, 48, v0
	v_lshl_add_u64 v[2:3], s[4:5], 0, v[192:193]
	s_mov_b64 s[14:15], 0x4488000
	s_add_i32 s9, s9, s8
	v_lshlrev_b32_e32 v0, 4, v0
	v_lshl_add_u64 v[66:67], v[2:3], 0, s[14:15]
	s_mul_hi_i32 s19, s9, 0x1400
	s_mul_i32 s28, s9, 0x1400
	s_mul_hi_i32 s14, s9, 0x300
	s_mulk_i32 s9, 0x300
	v_and_b32_e32 v0, 16, v0
	v_or_b32_e32 v68, s9, v0
	s_ashr_i32 s9, s8, 31
	v_mov_b32_e32 v69, s14
	s_add_u32 s8, s97, s8
	v_readlane_b32 s14, v254, 33
	s_addc_u32 s9, s14, s9
	v_cmp_eq_u32_e32 vcc, 32, v1
	v_mov_b32_e32 v1, 0x3e38aa3b
	s_mul_i32 s14, s9, 0x1400
	s_mul_hi_u32 s15, s8, 0x1400
	s_mulk_i32 s9, 0x300
	s_mul_hi_u32 s20, s8, 0x300
	v_readlane_b32 s46, v254, 29
	v_or_b32_e32 v5, 0x940, v4
	v_cndmask_b32_e32 v88, 1.0, v1, vcc
	v_cndmask_b32_e64 v1, 0, 1, s[42:43]
	s_add_i32 s15, s15, s14
	s_mul_i32 s14, s8, 0x1400
	s_add_i32 s20, s20, s9
	s_mulk_i32 s8, 0x300
	v_readlane_b32 s3, v254, 31
	v_readlane_b32 s33, v254, 32
	v_readlane_b32 s47, v254, 30
	s_mul_i32 s18, s88, 0x14000
	s_mov_b32 s62, s2
	v_lshl_or_b32 v87, v86, 5, v4
	v_and_b32_e32 v89, v1, v6
	v_cndmask_b32_e64 v90, v5, v8, s[42:43]
	v_or_b32_e32 v70, s8, v0
	v_mov_b32_e32 v71, s20
	v_readlane_b32 s69, v253, 17
	v_readlane_b32 s70, v253, 18
	v_readlane_b32 s71, v253, 19
	v_readlane_b32 s72, v253, 20
	v_readlane_b32 s73, v253, 21
	v_readlane_b32 s74, v253, 22
	v_readlane_b32 s75, v253, 23
	v_readlane_b32 s76, v253, 24
	v_readlane_b32 s77, v253, 25
	v_readlane_b32 s78, v253, 26
	v_readlane_b32 s79, v253, 27
	s_waitcnt vmcnt(0)
	s_branch .LBB0_406

; template <int NTK>
; __device__ __forceinline__ void pp_elem(const int (&toks)[NTK], bf16_t* PROJ, bf16_t* KC, const float2* rope, const float* dqn, const float* dkn, int lane) {
;     ...
;     for (int k = 0; k < NTK; ++k) { const int tok = toks[k], pos = tok & (SEQ - 1); const bf16_t* row = PROJ + (size_t)tok * PPITCH + e0;
;         const int pe = isD ? (sec ? (pos & 63) : (pos >> 6)) : pos; const f32x4* rq = (const f32x4*)(rope + pe * 16 + c * 8);
;         if (active) { xa[k] = *(const u32x4*)row; xb[k] = *(const u32x4*)(row + 16); } else { xa[k] = (u32x4){0u, 0u, 0u, 0u}; xb[k] = xa[k]; }
;     ...
;         if (active) {
;             if (isC) { bf16_t* kc = KC + (size_t)tok * 384 + 64 + c * 8;
; #pragma unroll
;                 for (int hh = 0; hh < 4; ++hh) { *(u32x4*)(kc + hh * 96) = oa; *(u32x4*)(kc + hh * 96 + 16) = ob; } }
;             else { bf16_t* row = PROJ + (size_t)tok * PPITCH + e0; *(u32x4*)row = oa; *(u32x4*)(row + 16) = ob; } }
.LBB0_420:
	s_or_b64 exec, exec, s[20:21]
	s_waitcnt vmcnt(0)
	s_mov_b64 s[8:9], 0
.LBB0_421:
	s_and_b64 vcc, exec, s[8:9]
	s_cbranch_vccz .LBB0_405
	s_mov_b64 s[20:21], 0
	v_mov_b32_e32 v72, 1.0
	v_mov_b64_e32 v[20:21], s[6:7]
	v_mov_b32_e32 v0, v86
	v_mov_b32_e32 v192, v87
	s_and_saveexec_b64 s[8:9], s[10:11]
	s_and_b64 s[20:21], s[42:43], exec
	v_mov_b64_e32 v[20:21], v[64:65]
	v_mov_b32_e32 v72, v88
	v_mov_b32_e32 v0, v89
	v_mov_b32_e32 v192, v90
	s_or_b64 exec, exec, s[8:9]
	v_mov_b32_e32 v56, 0
	v_mov_b32_e32 v57, 0
	v_mov_b32_e32 v58, 0
	v_mov_b32_e32 v59, 0
	v_mov_b32_e32 v60, 0
	v_mov_b32_e32 v61, 0
	v_mov_b32_e32 v62, 0
	v_mov_b32_e32 v63, 0
	s_and_saveexec_b64 s[8:9], s[38:39]
	s_cbranch_execz .LBB0_426
	s_add_u32 s22, s4, s14
	s_addc_u32 s23, s5, s15
	v_lshl_add_u64 v[2:3], v[192:193], 1, s[22:23]
	v_add_co_u32_e32 v2, vcc, 0x84c8000, v2
	s_nop 1
	v_addc_co_u32_e32 v3, vcc, 0, v3, vcc
	global_load_dwordx4 v[60:63], v[2:3], off
	global_load_dwordx4 v[56:59], v[2:3], off offset:32

; __device__ __forceinline__ float bf2f(bf16_t b) { return __uint_as_float((unsigned)b << 16); }
; __device__ __forceinline__ void pp_mla_lds(int tok0, int hh, const bf16_t* PROJ, bf16_t* QC, bf16_t* KC, bf16_t* VC, const float2* rope, const char* Lq, const char* Lkv, const float* cqn, const float* ckvn, int lane) {
;     const int m = lane & 15, quad = lane >> 4, tok = tok0 + m, pos = tok & (SEQ - 1);
;     const bf16_t* crow_ = PROJ + (size_t)tok * PPITCH + PC;
;     bf16x8 aq[6], ak[4]; float ssq_ = 0.f, ssk_ = 0.f;
; #pragma unroll
;     for (int ks = 0; ks < 6; ++ks) aq[ks] = *(const bf16x8*)(crow_ + ks * 32 + quad * 8);
; #pragma unroll
;     for (int ks = 0; ks < 4; ++ks) ak[ks] = *(const bf16x8*)(crow_ + 192 + ks * 32 + quad * 8);
; #pragma unroll
;     for (int ks = 0; ks < 6; ++ks)
; #pragma unroll
;         for (int e = 0; e < 8; ++e) { const float x = bf2f((bf16_t)aq[ks][e]); ssq_ += x * x; }
; #pragma unroll
;     for (int ks = 0; ks < 4; ++ks)
; #pragma unroll
;         for (int e = 0; e < 8; ++e) { const float x = bf2f((bf16_t)ak[ks][e]); ssk_ += x * x; }
;     ssq_ += __shfl_xor(ssq_, 16); ssq_ += __shfl_xor(ssq_, 32); ssk_ += __shfl_xor(ssk_, 16); ssk_ += __shfl_xor(ssk_, 32);
;     const float rq = __builtin_amdgcn_rsqf(ssq_ * (1.f / 192.f) + EPS), rk = __builtin_amdgcn_rsqf(ssk_ * (1.f / 128.f) + EPS);
.LBB0_500:
	v_mov_b64_e32 v[0:1], s[6:7]
	v_mad_i64_i32 v[0:1], s[4:5], v84, s56, v[0:1]
	v_lshl_add_u64 v[0:1], v[0:1], 0, v[192:193]
	v_add_co_u32_e32 v4, vcc, 0x1000, v0
	s_mov_b64 s[4:5], 0x1000
	s_nop 0
	v_addc_co_u32_e32 v5, vcc, 0, v1, vcc
	v_lshl_add_u64 v[2:3], v[0:1], 0, s[4:5]
	global_load_dwordx4 v[16:19], v[4:5], off
	global_load_dwordx4 v[20:23], v[2:3], off offset:64
	global_load_dwordx4 v[24:27], v[2:3], off offset:128
	global_load_dwordx4 v[28:31], v[2:3], off offset:192
	global_load_dwordx4 v[32:35], v[2:3], off offset:256
	global_load_dwordx4 v[36:39], v[2:3], off offset:320
	s_mov_b64 s[4:5], 0x1180
	v_lshl_add_u64 v[6:7], v[0:1], 0, s[4:5]
	global_load_dwordx4 v[64:67], v[4:5], off offset:384
	global_load_dwordx4 v[52:55], v[6:7], off offset:64
	global_load_dwordx4 v[0:3], v[6:7], off offset:128
	s_nop 0
	global_load_dwordx4 v[4:7], v[6:7], off offset:192
	s_nop 0
	global_load_dwordx4 v[96:99], v[72:73], off offset:16
	global_load_dwordx4 v[100:103], v[72:73], off
	global_load_dwordx4 v[104:107], v[72:73], off offset:144
	global_load_dwordx4 v[108:111], v[72:73], off offset:128
	global_load_dwordx4 v[112:115], v[72:73], off offset:272
	global_load_dwordx4 v[116:119], v[72:73], off offset:256
	global_load_dwordx4 v[120:123], v[72:73], off offset:400
	global_load_dwordx4 v[124:127], v[72:73], off offset:384
	global_load_dwordx4 v[128:131], v[72:73], off offset:528
	global_load_dwordx4 v[132:135], v[72:73], off offset:512
	global_load_dwordx4 v[136:139], v[72:73], off offset:656
	global_load_dwordx4 v[140:143], v[72:73], off offset:640
	global_load_dwordx4 v[40:43], v[74:75], off offset:16
	global_load_dwordx4 v[12:15], v[74:75], off
	global_load_dwordx4 v[48:51], v[74:75], off offset:144
	global_load_dwordx4 v[8:11], v[74:75], off offset:128
	global_load_dwordx4 v[60:63], v[74:75], off offset:272
	global_load_dwordx4 v[68:71], v[74:75], off offset:256
	global_load_dwordx4 v[44:47], v[74:75], off offset:400
	global_load_dwordx4 v[56:59], v[74:75], off offset:384
	v_ashrrev_i32_e32 v85, 31, v84
	s_add_i32 s8, s8, s25
	s_cmp_ge_i32 s8, s19
	s_waitcnt vmcnt(0) lgkmcnt(0)
	v_and_b32_e32 v155, 0xffff0000, v16
	v_lshlrev_b32_e32 v154, 16, v16
	v_and_b32_e32 v151, 0xffff0000, v17
	v_lshlrev_b32_e32 v150, 16, v17
	v_pk_mul_f32 v[16:17], v[154:155], v[154:155]
	v_pk_mul_f32 v[152:153], v[150:151], v[150:151]
	v_add_f32_e32 v16, v16, v17
	v_and_b32_e32 v149, 0xffff0000, v18
	v_lshlrev_b32_e32 v148, 16, v18
	v_add_f32_e32 v16, v152, v16
	v_and_b32_e32 v145, 0xffff0000, v19
	v_lshlrev_b32_e32 v144, 16, v19
	v_pk_mul_f32 v[18:19], v[148:149], v[148:149]
	v_add_f32_e32 v16, v153, v16
	v_add_f32_e32 v16, v18, v16
	v_pk_mul_f32 v[146:147], v[144:145], v[144:145]
	v_add_f32_e32 v16, v19, v16
	v_and_b32_e32 v167, 0xffff0000, v20
	v_lshlrev_b32_e32 v166, 16, v20
	v_add_f32_e32 v16, v146, v16
	v_and_b32_e32 v163, 0xffff0000, v21
	v_lshlrev_b32_e32 v162, 16, v21
	v_pk_mul_f32 v[20:21], v[166:167], v[166:167]
	v_add_f32_e32 v16, v147, v16
	v_add_f32_e32 v16, v20, v16
	v_pk_mul_f32 v[164:165], v[162:163], v[162:163]
	v_add_f32_e32 v16, v21, v16
	v_and_b32_e32 v161, 0xffff0000, v22
	v_lshlrev_b32_e32 v160, 16, v22
	v_add_f32_e32 v16, v164, v16
	v_and_b32_e32 v157, 0xffff0000, v23
	v_lshlrev_b32_e32 v156, 16, v23
	v_pk_mul_f32 v[22:23], v[160:161], v[160:161]
	v_add_f32_e32 v16, v165, v16
	v_add_f32_e32 v16, v22, v16
	v_pk_mul_f32 v[158:159], v[156:157], v[156:157]
	v_add_f32_e32 v16, v23, v16
	v_and_b32_e32 v179, 0xffff0000, v24
	v_lshlrev_b32_e32 v178, 16, v24
	v_add_f32_e32 v16, v158, v16
	v_and_b32_e32 v175, 0xffff0000, v25
	v_lshlrev_b32_e32 v174, 16, v25
	v_pk_mul_f32 v[24:25], v[178:179], v[178:179]
	v_add_f32_e32 v16, v159, v16
	v_add_f32_e32 v16, v24, v16
	v_pk_mul_f32 v[176:177], v[174:175], v[174:175]
	v_add_f32_e32 v16, v25, v16
	v_and_b32_e32 v173, 0xffff0000, v26
	v_lshlrev_b32_e32 v172, 16, v26
	v_add_f32_e32 v16, v176, v16
	v_and_b32_e32 v169, 0xffff0000, v27
	v_lshlrev_b32_e32 v168, 16, v27
	v_pk_mul_f32 v[26:27], v[172:173], v[172:173]
	v_add_f32_e32 v16, v177, v16
	v_add_f32_e32 v16, v26, v16
	v_pk_mul_f32 v[170:171], v[168:169], v[168:169]
	v_add_f32_e32 v16, v27, v16
	v_and_b32_e32 v187, 0xffff0000, v29
	v_lshlrev_b32_e32 v186, 16, v29
	v_and_b32_e32 v29, 0xffff0000, v28
	v_lshlrev_b32_e32 v28, 16, v28
	v_add_f32_e32 v16, v170, v16
	v_pk_mul_f32 v[190:191], v[28:29], v[28:29]
	v_add_f32_e32 v16, v171, v16
	v_add_f32_e32 v16, v190, v16
	v_pk_mul_f32 v[188:189], v[186:187], v[186:187]
	v_add_f32_e32 v16, v191, v16
	v_and_b32_e32 v181, 0xffff0000, v31
	v_lshlrev_b32_e32 v180, 16, v31
	v_and_b32_e32 v31, 0xffff0000, v30
	v_lshlrev_b32_e32 v30, 16, v30
	v_add_f32_e32 v16, v188, v16
	v_pk_mul_f32 v[184:185], v[30:31], v[30:31]
	v_add_f32_e32 v16, v189, v16
	v_add_f32_e32 v16, v184, v16
	v_pk_mul_f32 v[182:183], v[180:181], v[180:181]
	v_add_f32_e32 v16, v185, v16
	v_and_b32_e32 v201, 0xffff0000, v33
	v_lshlrev_b32_e32 v200, 16, v33
	v_and_b32_e32 v33, 0xffff0000, v32
	v_lshlrev_b32_e32 v32, 16, v32
	v_add_f32_e32 v16, v182, v16
	v_pk_mul_f32 v[204:205], v[32:33], v[32:33]
	v_add_f32_e32 v16, v183, v16
	v_add_f32_e32 v16, v204, v16
	v_pk_mul_f32 v[202:203], v[200:201], v[200:201]
	v_add_f32_e32 v16, v205, v16
	v_and_b32_e32 v195, 0xffff0000, v35
	v_lshlrev_b32_e32 v194, 16, v35
	v_and_b32_e32 v35, 0xffff0000, v34
	v_lshlrev_b32_e32 v34, 16, v34
	v_add_f32_e32 v16, v202, v16
	v_pk_mul_f32 v[198:199], v[34:35], v[34:35]
	v_add_f32_e32 v16, v203, v16
	v_add_f32_e32 v16, v198, v16
	v_pk_mul_f32 v[196:197], v[194:195], v[194:195]
	v_add_f32_e32 v16, v199, v16
	v_and_b32_e32 v213, 0xffff0000, v37
	v_lshlrev_b32_e32 v212, 16, v37
	v_and_b32_e32 v37, 0xffff0000, v36
	v_lshlrev_b32_e32 v36, 16, v36
	v_add_f32_e32 v16, v196, v16
	v_pk_mul_f32 v[216:217], v[36:37], v[36:37]
	v_add_f32_e32 v16, v197, v16
	v_add_f32_e32 v16, v216, v16
	v_pk_mul_f32 v[214:215], v[212:213], v[212:213]
	v_add_f32_e32 v16, v217, v16
	v_and_b32_e32 v207, 0xffff0000, v39
	v_lshlrev_b32_e32 v206, 16, v39
	v_and_b32_e32 v39, 0xffff0000, v38
	v_lshlrev_b32_e32 v38, 16, v38
	v_add_f32_e32 v16, v214, v16
	v_pk_mul_f32 v[210:211], v[38:39], v[38:39]
	v_add_f32_e32 v16, v215, v16
	v_add_f32_e32 v16, v210, v16
	v_pk_mul_f32 v[208:209], v[206:207], v[206:207]
	v_add_f32_e32 v16, v211, v16
	v_add_f32_e32 v16, v208, v16
	v_add_f32_e32 v16, v209, v16
	ds_bpermute_b32 v17, v86, v16
	s_waitcnt lgkmcnt(0)
; __device__ __forceinline__ unsigned cvt_pk_bf16(float lo, float hi) { typedef float f2 __attribute__((ext_vector_type(2))); typedef __bf16 b2 __attribute__((ext_vector_type(2))); f2 v = {lo, hi}; b2 b = __builtin_convertvector(v, b2); return __builtin_bit_cast(unsigned, b); }
; __device__ __forceinline__ float bf2f(bf16_t b) { return __uint_as_float((unsigned)b << 16); }
; __device__ __forceinline__ void pp_mla_lds(int tok0, int hh, const bf16_t* PROJ, bf16_t* QC, bf16_t* KC, bf16_t* VC, const float2* rope, const char* Lq, const char* Lkv, const float* cqn, const float* ckvn, int lane) {
;     ...
;     ssq_ += __shfl_xor(ssq_, 16); ssq_ += __shfl_xor(ssq_, 32); ssk_ += __shfl_xor(ssk_, 16); ssk_ += __shfl_xor(ssk_, 32);
;     const float rq = __builtin_amdgcn_rsqf(ssq_ * (1.f / 192.f) + EPS), rk = __builtin_amdgcn_rsqf(ssk_ * (1.f / 128.f) + EPS);
; #pragma unroll
;     for (int ks = 0; ks < 6; ++ks) { u32x4 w; const f32x4 ga = *(const f32x4*)(cqn + ks * 32 + quad * 8), gb = *(const f32x4*)(cqn + ks * 32 + quad * 8 + 4);
; #pragma unroll
;         for (int e = 0; e < 4; ++e) { const float g0 = e < 2 ? ga[2 * e] : gb[2 * e - 4], g1 = e < 2 ? ga[2 * e + 1] : gb[2 * e - 3]; w[e] = cvt_pk_bf16(bf2f((bf16_t)aq[ks][2 * e]) * rq * g0, bf2f((bf16_t)aq[ks][2 * e + 1]) * rq * g1); }
;         aq[ks] = __builtin_bit_cast(bf16x8, w); }
; #pragma unroll
;     for (int ks = 0; ks < 4; ++ks) { u32x4 w; const f32x4 ga = *(const f32x4*)(ckvn + ks * 32 + quad * 8), gb = *(const f32x4*)(ckvn + ks * 32 + quad * 8 + 4);
; #pragma unroll
;         for (int e = 0; e < 4; ++e) { const float g0 = e < 2 ? ga[2 * e] : gb[2 * e - 4], g1 = e < 2 ? ga[2 * e + 1] : gb[2 * e - 3]; w[e] = cvt_pk_bf16(bf2f((bf16_t)ak[ks][2 * e]) * rk * g0, bf2f((bf16_t)ak[ks][2 * e + 1]) * rk * g1); }
;         ak[ks] = __builtin_bit_cast(bf16x8, w); }
	v_add_f32_e32 v16, v16, v17
	ds_bpermute_b32 v17, v87, v16
	s_waitcnt lgkmcnt(0)
	v_add_f32_e32 v16, v16, v17
	v_fmamk_f32 v16, v16, 0x3baaaaab, v242
	v_rsq_f32_e32 v146, v16
	s_nop 0
	v_pk_mul_f32 v[16:17], v[146:147], v[36:37] op_sel_hi:[0,1]
	v_pk_mul_f32 v[18:19], v[146:147], v[212:213] op_sel_hi:[0,1]
	v_pk_mul_f32 v[16:17], v[140:141], v[16:17]
	v_pk_mul_f32 v[18:19], v[142:143], v[18:19]
	v_cvt_pk_bf16_f32 v16, v16, v17
	v_cvt_pk_bf16_f32 v17, v18, v19
	v_pk_mul_f32 v[18:19], v[146:147], v[38:39] op_sel_hi:[0,1]
	v_pk_mul_f32 v[20:21], v[146:147], v[206:207] op_sel_hi:[0,1]
	v_pk_mul_f32 v[18:19], v[136:137], v[18:19]
	v_pk_mul_f32 v[20:21], v[138:139], v[20:21]
	v_cvt_pk_bf16_f32 v18, v18, v19
	v_cvt_pk_bf16_f32 v19, v20, v21
	v_pk_mul_f32 v[20:21], v[146:147], v[32:33] op_sel_hi:[0,1]
	v_pk_mul_f32 v[22:23], v[146:147], v[200:201] op_sel_hi:[0,1]
	v_pk_mul_f32 v[20:21], v[132:133], v[20:21]
	v_pk_mul_f32 v[22:23], v[134:135], v[22:23]
	v_cvt_pk_bf16_f32 v20, v20, v21
	v_cvt_pk_bf16_f32 v21, v22, v23
	v_pk_mul_f32 v[22:23], v[146:147], v[34:35] op_sel_hi:[0,1]
	v_pk_mul_f32 v[24:25], v[146:147], v[194:195] op_sel_hi:[0,1]
	v_pk_mul_f32 v[22:23], v[128:129], v[22:23]
	v_pk_mul_f32 v[24:25], v[130:131], v[24:25]
	v_cvt_pk_bf16_f32 v22, v22, v23
	v_cvt_pk_bf16_f32 v23, v24, v25
	v_pk_mul_f32 v[24:25], v[146:147], v[28:29] op_sel_hi:[0,1]
	v_pk_mul_f32 v[26:27], v[146:147], v[186:187] op_sel_hi:[0,1]
	v_pk_mul_f32 v[24:25], v[124:125], v[24:25]
	v_pk_mul_f32 v[26:27], v[126:127], v[26:27]
	v_cvt_pk_bf16_f32 v24, v24, v25
	v_cvt_pk_bf16_f32 v25, v26, v27
	v_pk_mul_f32 v[26:27], v[146:147], v[30:31] op_sel_hi:[0,1]
	v_pk_mul_f32 v[28:29], v[146:147], v[180:181] op_sel_hi:[0,1]
	v_pk_mul_f32 v[26:27], v[120:121], v[26:27]
	v_pk_mul_f32 v[28:29], v[122:123], v[28:29]
	v_cvt_pk_bf16_f32 v26, v26, v27
	v_cvt_pk_bf16_f32 v27, v28, v29
	v_pk_mul_f32 v[28:29], v[146:147], v[178:179] op_sel_hi:[0,1]
	v_pk_mul_f32 v[30:31], v[146:147], v[174:175] op_sel_hi:[0,1]
	v_pk_mul_f32 v[28:29], v[116:117], v[28:29]
	v_pk_mul_f32 v[30:31], v[118:119], v[30:31]
	v_cvt_pk_bf16_f32 v28, v28, v29
	v_cvt_pk_bf16_f32 v29, v30, v31
	v_pk_mul_f32 v[30:31], v[146:147], v[172:173] op_sel_hi:[0,1]
	v_pk_mul_f32 v[32:33], v[146:147], v[168:169] op_sel_hi:[0,1]
	v_pk_mul_f32 v[30:31], v[112:113], v[30:31]
	v_pk_mul_f32 v[32:33], v[114:115], v[32:33]
	v_cvt_pk_bf16_f32 v30, v30, v31
	v_cvt_pk_bf16_f32 v31, v32, v33
	v_pk_mul_f32 v[32:33], v[146:147], v[166:167] op_sel_hi:[0,1]
	v_pk_mul_f32 v[34:35], v[146:147], v[162:163] op_sel_hi:[0,1]
	v_pk_mul_f32 v[32:33], v[108:109], v[32:33]
	v_pk_mul_f32 v[34:35], v[110:111], v[34:35]
	v_pk_mul_f32 v[36:37], v[146:147], v[156:157] op_sel_hi:[0,1]
	v_cvt_pk_bf16_f32 v32, v32, v33
	v_cvt_pk_bf16_f32 v33, v34, v35
	v_pk_mul_f32 v[34:35], v[146:147], v[160:161] op_sel_hi:[0,1]
	v_pk_mul_f32 v[36:37], v[106:107], v[36:37]
	v_and_b32_e32 v107, 0xffff0000, v65
	v_lshlrev_b32_e32 v106, 16, v65
	v_and_b32_e32 v65, 0xffff0000, v64
	v_lshlrev_b32_e32 v64, 16, v64
	v_pk_mul_f32 v[34:35], v[104:105], v[34:35]
	v_pk_mul_f32 v[110:111], v[64:65], v[64:65]
	v_cvt_pk_bf16_f32 v34, v34, v35
	v_cvt_pk_bf16_f32 v35, v36, v37
	v_pk_mul_f32 v[36:37], v[146:147], v[154:155] op_sel_hi:[0,1]
	v_pk_mul_f32 v[108:109], v[106:107], v[106:107]
	v_add_f32_e32 v110, v110, v111
	v_pk_mul_f32 v[36:37], v[100:101], v[36:37]
	v_and_b32_e32 v101, 0xffff0000, v67
	v_lshlrev_b32_e32 v100, 16, v67
	v_and_b32_e32 v67, 0xffff0000, v66
	v_lshlrev_b32_e32 v66, 16, v66
	v_add_f32_e32 v108, v108, v110
	v_pk_mul_f32 v[104:105], v[66:67], v[66:67]
	v_add_f32_e32 v108, v109, v108
	v_pk_mul_f32 v[38:39], v[146:147], v[150:151] op_sel_hi:[0,1]
	v_add_f32_e32 v104, v104, v108
	v_pk_mul_f32 v[38:39], v[102:103], v[38:39]
	v_pk_mul_f32 v[102:103], v[100:101], v[100:101]
	v_add_f32_e32 v104, v105, v104
	v_and_b32_e32 v119, 0xffff0000, v53
	v_lshlrev_b32_e32 v118, 16, v53
	v_and_b32_e32 v53, 0xffff0000, v52
	v_lshlrev_b32_e32 v52, 16, v52
	v_add_f32_e32 v102, v102, v104
	v_pk_mul_f32 v[122:123], v[52:53], v[52:53]
	v_add_f32_e32 v102, v103, v102
	v_add_f32_e32 v102, v122, v102
	v_pk_mul_f32 v[120:121], v[118:119], v[118:119]
	v_add_f32_e32 v102, v123, v102
	v_and_b32_e32 v113, 0xffff0000, v55
	v_lshlrev_b32_e32 v112, 16, v55
	v_and_b32_e32 v55, 0xffff0000, v54
	v_lshlrev_b32_e32 v54, 16, v54
	v_add_f32_e32 v102, v120, v102
	v_pk_mul_f32 v[116:117], v[54:55], v[54:55]
	v_add_f32_e32 v102, v121, v102
	v_add_f32_e32 v102, v116, v102
	v_pk_mul_f32 v[114:115], v[112:113], v[112:113]
	v_add_f32_e32 v102, v117, v102
	v_and_b32_e32 v139, 0xffff0000, v1
	v_lshlrev_b32_e32 v138, 16, v1
	v_and_b32_e32 v1, 0xffff0000, v0
	v_lshlrev_b32_e32 v0, 16, v0
	v_add_f32_e32 v102, v114, v102
	v_pk_mul_f32 v[142:143], v[0:1], v[0:1]
	v_add_f32_e32 v102, v115, v102
	v_add_f32_e32 v102, v142, v102
	v_pk_mul_f32 v[140:141], v[138:139], v[138:139]
	v_add_f32_e32 v102, v143, v102
	v_and_b32_e32 v133, 0xffff0000, v3
	v_lshlrev_b32_e32 v132, 16, v3
	v_and_b32_e32 v3, 0xffff0000, v2
	v_lshlrev_b32_e32 v2, 16, v2
	v_add_f32_e32 v102, v140, v102
	v_pk_mul_f32 v[136:137], v[2:3], v[2:3]
	v_add_f32_e32 v102, v141, v102
	v_add_f32_e32 v102, v136, v102
	v_pk_mul_f32 v[134:135], v[132:133], v[132:133]
	v_add_f32_e32 v102, v137, v102
	v_and_b32_e32 v127, 0xffff0000, v5
	v_lshlrev_b32_e32 v126, 16, v5
	v_and_b32_e32 v5, 0xffff0000, v4
	v_lshlrev_b32_e32 v4, 16, v4
	v_add_f32_e32 v102, v134, v102
	v_cvt_pk_bf16_f32 v36, v36, v37
	v_cvt_pk_bf16_f32 v37, v38, v39
	v_pk_mul_f32 v[38:39], v[146:147], v[148:149] op_sel_hi:[0,1]
	v_pk_mul_f32 v[130:131], v[4:5], v[4:5]
	v_add_f32_e32 v102, v135, v102
	v_pk_mul_f32 v[38:39], v[96:97], v[38:39]
	v_pk_mul_f32 v[96:97], v[146:147], v[144:145] op_sel_hi:[0,1]
	v_add_f32_e32 v102, v130, v102
	v_pk_mul_f32 v[96:97], v[98:99], v[96:97]
	v_pk_mul_f32 v[128:129], v[126:127], v[126:127]
	v_add_f32_e32 v102, v131, v102
	v_cvt_pk_bf16_f32 v38, v38, v39
	v_cvt_pk_bf16_f32 v39, v96, v97
	v_and_b32_e32 v97, 0xffff0000, v7
	v_lshlrev_b32_e32 v96, 16, v7
	v_and_b32_e32 v7, 0xffff0000, v6
	v_lshlrev_b32_e32 v6, 16, v6
	v_add_f32_e32 v102, v128, v102
	v_pk_mul_f32 v[124:125], v[6:7], v[6:7]
	v_add_f32_e32 v102, v129, v102
	v_add_f32_e32 v102, v124, v102
	v_pk_mul_f32 v[98:99], v[96:97], v[96:97]
	v_add_f32_e32 v102, v125, v102
	v_add_f32_e32 v98, v98, v102
	v_add_f32_e32 v98, v99, v98
	ds_bpermute_b32 v99, v86, v98
	s_waitcnt lgkmcnt(0)
; __device__ __forceinline__ unsigned cvt_pk_bf16(float lo, float hi) { typedef float f2 __attribute__((ext_vector_type(2))); typedef __bf16 b2 __attribute__((ext_vector_type(2))); f2 v = {lo, hi}; b2 b = __builtin_convertvector(v, b2); return __builtin_bit_cast(unsigned, b); }
; __device__ __forceinline__ float bf2f(bf16_t b) { return __uint_as_float((unsigned)b << 16); }
; #define MFMA16(a, b, c) __builtin_amdgcn_mfma_f32_16x16x32_bf16((a), (b), (c), 0, 0, 0)
; __device__ __forceinline__ void pp_mla_lds(int tok0, int hh, const bf16_t* PROJ, bf16_t* QC, bf16_t* KC, bf16_t* VC, const float2* rope, const char* Lq, const char* Lkv, const float* cqn, const float* ckvn, int lane) {
;     ...
;     for (int ks = 0; ks < 4; ++ks) { u32x4 w; const f32x4 ga = *(const f32x4*)(ckvn + ks * 32 + quad * 8), gb = *(const f32x4*)(ckvn + ks * 32 + quad * 8 + 4);
; #pragma unroll
;         for (int e = 0; e < 4; ++e) { const float g0 = e < 2 ? ga[2 * e] : gb[2 * e - 4], g1 = e < 2 ? ga[2 * e + 1] : gb[2 * e - 3]; w[e] = cvt_pk_bf16(bf2f((bf16_t)ak[ks][2 * e]) * rk * g0, bf2f((bf16_t)ak[ks][2 * e + 1]) * rk * g1); }
;         ak[ks] = __builtin_bit_cast(bf16x8, w); }
;     const float qs = 0.10206207261596577f * LOG2E;
;     f32x4 cs4[2];
; #pragma unroll
;     for (int q = 0; q < 2; ++q) cs4[q] = *(const f32x4*)(rope + pos * 16 + quad * 4 + 2 * q);
;     {
;         {   f32x4 acc[6];
; #pragma unroll
;             for (int nt = 0; nt < 6; ++nt) { acc[nt] = (f32x4){0.f, 0.f, 0.f, 0.f}; const char* wr_ = Lq + (nt * 16 + m) * 400 + quad * 16;
; #pragma unroll
;                 for (int ks = 0; ks < 6; ++ks) acc[nt] = MFMA16(*(const bf16x8*)(wr_ + ks * 64), aq[ks], acc[nt]); }
	v_add_f32_e32 v98, v98, v99
	ds_bpermute_b32 v99, v87, v98
	s_waitcnt lgkmcnt(0)
	v_add_f32_e32 v98, v98, v99
	v_fmamk_f32 v98, v98, 0x3c000000, v242
	v_rsq_f32_e32 v98, v98
	s_nop 0
	v_pk_mul_f32 v[6:7], v[98:99], v[6:7] op_sel_hi:[0,1]
	v_pk_mul_f32 v[6:7], v[44:45], v[6:7]
	v_pk_mul_f32 v[44:45], v[98:99], v[52:53] op_sel_hi:[0,1]
	v_pk_mul_f32 v[8:9], v[8:9], v[44:45]
	v_pk_mul_f32 v[44:45], v[98:99], v[118:119] op_sel_hi:[0,1]
	v_pk_mul_f32 v[10:11], v[10:11], v[44:45]
	v_cvt_pk_bf16_f32 v8, v8, v9
	v_cvt_pk_bf16_f32 v9, v10, v11
	v_pk_mul_f32 v[10:11], v[98:99], v[54:55] op_sel_hi:[0,1]
	v_pk_mul_f32 v[44:45], v[98:99], v[112:113] op_sel_hi:[0,1]
	v_pk_mul_f32 v[10:11], v[48:49], v[10:11]
	v_pk_mul_f32 v[44:45], v[50:51], v[44:45]
	v_cvt_pk_bf16_f32 v10, v10, v11
	v_cvt_pk_bf16_f32 v11, v44, v45
	v_pk_mul_f32 v[44:45], v[98:99], v[64:65] op_sel_hi:[0,1]
	v_pk_mul_f32 v[12:13], v[12:13], v[44:45]
	v_pk_mul_f32 v[44:45], v[98:99], v[106:107] op_sel_hi:[0,1]
	v_pk_mul_f32 v[14:15], v[14:15], v[44:45]
	v_cvt_pk_bf16_f32 v12, v12, v13
	v_cvt_pk_bf16_f32 v13, v14, v15
	v_pk_mul_f32 v[14:15], v[98:99], v[66:67] op_sel_hi:[0,1]
	v_pk_mul_f32 v[14:15], v[40:41], v[14:15]
	v_pk_mul_f32 v[40:41], v[98:99], v[100:101] op_sel_hi:[0,1]
	v_pk_mul_f32 v[40:41], v[42:43], v[40:41]
	v_cvt_pk_bf16_f32 v14, v14, v15
	v_cvt_pk_bf16_f32 v15, v40, v41
	v_pk_mul_f32 v[40:41], v[98:99], v[96:97] op_sel_hi:[0,1]
	v_pk_mul_f32 v[40:41], v[46:47], v[40:41]
	v_cvt_pk_bf16_f32 v6, v6, v7
	v_cvt_pk_bf16_f32 v7, v40, v41
	v_and_b32_e32 v40, 0x7ff0, v91
	v_lshlrev_b32_e32 v40, 3, v40
	v_mov_b32_e32 v41, v193
	v_lshl_add_u64 v[40:41], v[76:77], 0, v[40:41]
	global_load_dwordx4 v[44:47], v[40:41], off
	s_nop 0
	global_load_dwordx4 v[40:43], v[40:41], off offset:16
	ds_read_b128 v[48:51], v92
	ds_read_b128 v[52:55], v92 offset:64
	s_waitcnt lgkmcnt(0)
	v_mfma_f32_16x16x32_bf16 v[48:51], v[48:51], v[36:39], 0
	v_mul_f32_e64 v4, v98, v4
	v_mul_f32_e64 v5, v98, v5
	v_pk_mul_f32 v[4:5], v[56:57], v[4:5]
	v_pk_mul_f32 v[56:57], v[98:99], v[126:127] op_sel_hi:[0,1]
	v_mfma_f32_16x16x32_bf16 v[48:51], v[52:55], v[32:35], v[48:51]
	ds_read_b128 v[52:55], v92 offset:128
	v_pk_mul_f32 v[56:57], v[58:59], v[56:57]
	v_cvt_pk_bf16_f32 v4, v4, v5
	v_cvt_pk_bf16_f32 v5, v56, v57
	ds_read_b128 v[56:59], v92 offset:6464
	s_waitcnt lgkmcnt(0)
	v_mfma_f32_16x16x32_bf16 v[48:51], v[52:55], v[28:31], v[48:51]
	ds_read_b128 v[52:55], v92 offset:192
	v_pk_mul_f32 v[2:3], v[98:99], v[2:3] op_sel_hi:[0,1]
	v_pk_mul_f32 v[2:3], v[60:61], v[2:3]
	v_pk_mul_f32 v[60:61], v[98:99], v[132:133] op_sel_hi:[0,1]
	v_pk_mul_f32 v[60:61], v[62:63], v[60:61]
	v_cvt_pk_bf16_f32 v2, v2, v3
	v_cvt_pk_bf16_f32 v3, v60, v61
	ds_read_b128 v[60:63], v92 offset:12864
	s_waitcnt lgkmcnt(0)
	v_mfma_f32_16x16x32_bf16 v[48:51], v[52:55], v[24:27], v[48:51]
	ds_read_b128 v[52:55], v92 offset:256
	v_pk_mul_f32 v[0:1], v[98:99], v[0:1] op_sel_hi:[0,1]
	v_pk_mul_f32 v[0:1], v[68:69], v[0:1]
	v_pk_mul_f32 v[68:69], v[98:99], v[138:139] op_sel_hi:[0,1]
	v_pk_mul_f32 v[68:69], v[70:71], v[68:69]
	v_cvt_pk_bf16_f32 v0, v0, v1
	v_cvt_pk_bf16_f32 v1, v68, v69
	ds_read_b128 v[68:71], v92 offset:25664
	s_waitcnt lgkmcnt(0)
	v_mfma_f32_16x16x32_bf16 v[48:51], v[52:55], v[20:23], v[48:51]
	ds_read_b128 v[52:55], v92 offset:320
	ds_read_b128 v[64:67], v93 offset:64
	v_add_u32_e32 v91, s59, v91
	s_waitcnt lgkmcnt(0)
	v_mfma_f32_16x16x32_bf16 v[48:51], v[52:55], v[16:19], v[48:51]
	ds_read_b128 v[52:55], v92 offset:6400
	s_waitcnt lgkmcnt(0)
	v_mfma_f32_16x16x32_bf16 v[52:55], v[52:55], v[36:39], 0
	v_mfma_f32_16x16x32_bf16 v[52:55], v[56:59], v[32:35], v[52:55]
	ds_read_b128 v[56:59], v92 offset:6528
	s_waitcnt lgkmcnt(0)
	v_mfma_f32_16x16x32_bf16 v[52:55], v[56:59], v[28:31], v[52:55]
	ds_read_b128 v[56:59], v92 offset:6592
	s_waitcnt lgkmcnt(0)
	v_mfma_f32_16x16x32_bf16 v[52:55], v[56:59], v[24:27], v[52:55]
	ds_read_b128 v[56:59], v92 offset:6656
	s_waitcnt lgkmcnt(0)
	v_mfma_f32_16x16x32_bf16 v[52:55], v[56:59], v[20:23], v[52:55]
	ds_read_b128 v[56:59], v92 offset:6720
	s_waitcnt lgkmcnt(0)
	v_mfma_f32_16x16x32_bf16 v[52:55], v[56:59], v[16:19], v[52:55]
	ds_read_b128 v[56:59], v92 offset:12800
	s_waitcnt lgkmcnt(0)
	v_mfma_f32_16x16x32_bf16 v[56:59], v[56:59], v[36:39], 0
	v_mfma_f32_16x16x32_bf16 v[56:59], v[60:63], v[32:35], v[56:59]
	ds_read_b128 v[60:63], v92 offset:12928
	s_waitcnt lgkmcnt(0)
	v_mfma_f32_16x16x32_bf16 v[56:59], v[60:63], v[28:31], v[56:59]
	ds_read_b128 v[60:63], v92 offset:12992
	s_waitcnt lgkmcnt(0)
	v_mfma_f32_16x16x32_bf16 v[56:59], v[60:63], v[24:27], v[56:59]
	ds_read_b128 v[60:63], v92 offset:13056
	s_waitcnt lgkmcnt(0)
	v_mfma_f32_16x16x32_bf16 v[56:59], v[60:63], v[20:23], v[56:59]
	ds_read_b128 v[60:63], v92 offset:13120
	s_waitcnt lgkmcnt(0)
	v_mfma_f32_16x16x32_bf16 v[56:59], v[60:63], v[16:19], v[56:59]
	ds_read_b128 v[60:63], v93
	s_waitcnt lgkmcnt(0)
	v_mfma_f32_16x16x32_bf16 v[60:63], v[60:63], v[36:39], 0
	v_mfma_f32_16x16x32_bf16 v[60:63], v[64:67], v[32:35], v[60:63]
	ds_read_b128 v[64:67], v93 offset:128
	s_waitcnt lgkmcnt(0)
	v_mfma_f32_16x16x32_bf16 v[60:63], v[64:67], v[28:31], v[60:63]
	ds_read_b128 v[64:67], v93 offset:192
	s_waitcnt lgkmcnt(0)
	v_mfma_f32_16x16x32_bf16 v[60:63], v[64:67], v[24:27], v[60:63]
	ds_read_b128 v[64:67], v93 offset:256
	s_waitcnt lgkmcnt(0)
	v_mfma_f32_16x16x32_bf16 v[60:63], v[64:67], v[20:23], v[60:63]
	ds_read_b128 v[64:67], v93 offset:320
	s_waitcnt lgkmcnt(0)
	v_mfma_f32_16x16x32_bf16 v[60:63], v[64:67], v[16:19], v[60:63]
	ds_read_b128 v[64:67], v92 offset:25600
	s_waitcnt lgkmcnt(0)
; __device__ __forceinline__ unsigned cvt_pk_bf16(float lo, float hi) { typedef float f2 __attribute__((ext_vector_type(2))); typedef __bf16 b2 __attribute__((ext_vector_type(2))); f2 v = {lo, hi}; b2 b = __builtin_convertvector(v, b2); return __builtin_bit_cast(unsigned, b); }
; #define MFMA16(a, b, c) __builtin_amdgcn_mfma_f32_16x16x32_bf16((a), (b), (c), 0, 0, 0)
; __device__ __forceinline__ void pp_mla_lds(int tok0, int hh, const bf16_t* PROJ, bf16_t* QC, bf16_t* KC, bf16_t* VC, const float2* rope, const char* Lq, const char* Lkv, const float* cqn, const float* ckvn, int lane) {
;     ...
;             for (int nt = 0; nt < 6; ++nt) { acc[nt] = (f32x4){0.f, 0.f, 0.f, 0.f}; const char* wr_ = Lq + (nt * 16 + m) * 400 + quad * 16;
; #pragma unroll
;                 for (int ks = 0; ks < 6; ++ks) acc[nt] = MFMA16(*(const bf16x8*)(wr_ + ks * 64), aq[ks], acc[nt]); }
; #pragma unroll
;             for (int j = 0; j < 4; ++j) { const float c = cs4[j >> 1][2 * (j & 1)], sn = cs4[j >> 1][2 * (j & 1) + 1]; const float x1 = acc[4][j], x2 = acc[5][j]; acc[4][j] = x1 * c - x2 * sn; acc[5][j] = x2 * c + x1 * sn; }
;             bf16_t* qo = QC + (size_t)tok * 384 + hh * 96 + quad * 4;
; #pragma unroll
;             for (int nt = 0; nt < 6; ++nt) { u32x2 w; w.x = cvt_pk_bf16(acc[nt][0] * qs, acc[nt][1] * qs); w.y = cvt_pk_bf16(acc[nt][2] * qs, acc[nt][3] * qs); *(u32x2*)(qo + nt * 16) = w; } }
;         {   f32x4 acc[8];
; #pragma unroll
;             for (int nt = 0; nt < 8; ++nt) { acc[nt] = (f32x4){0.f, 0.f, 0.f, 0.f}; const char* wr_ = Lkv + (nt * 16 + m) * 288 + quad * 16;
; #pragma unroll
;                 for (int ks = 0; ks < 4; ++ks) acc[nt] = MFMA16(*(const bf16x8*)(wr_ + ks * 64), ak[ks], acc[nt]); }
	v_mfma_f32_16x16x32_bf16 v[64:67], v[64:67], v[36:39], 0
	v_mfma_f32_16x16x32_bf16 v[64:67], v[68:71], v[32:35], v[64:67]
	ds_read_b128 v[68:71], v92 offset:25728
	s_waitcnt lgkmcnt(0)
	v_mfma_f32_16x16x32_bf16 v[64:67], v[68:71], v[28:31], v[64:67]
	ds_read_b128 v[68:71], v92 offset:25792
	s_waitcnt lgkmcnt(0)
	v_mfma_f32_16x16x32_bf16 v[64:67], v[68:71], v[24:27], v[64:67]
	ds_read_b128 v[68:71], v92 offset:25856
	s_waitcnt lgkmcnt(0)
	v_mfma_f32_16x16x32_bf16 v[64:67], v[68:71], v[20:23], v[64:67]
	ds_read_b128 v[68:71], v92 offset:25920
	s_waitcnt lgkmcnt(0)
	v_mfma_f32_16x16x32_bf16 v[64:67], v[68:71], v[16:19], v[64:67]
	ds_read_b128 v[68:71], v92 offset:32000
	s_waitcnt lgkmcnt(0)
	v_mfma_f32_16x16x32_bf16 v[36:39], v[68:71], v[36:39], 0
	ds_read_b128 v[68:71], v92 offset:32064
	s_waitcnt lgkmcnt(0)
	v_mfma_f32_16x16x32_bf16 v[32:35], v[68:71], v[32:35], v[36:39]
	s_nop 4
	ds_read_b128 v[36:39], v92 offset:32128
	s_waitcnt lgkmcnt(0)
	v_mfma_f32_16x16x32_bf16 v[28:31], v[36:39], v[28:31], v[32:35]
	s_nop 2
	ds_read_b128 v[32:35], v92 offset:32192
	s_waitcnt lgkmcnt(0)
	v_mfma_f32_16x16x32_bf16 v[24:27], v[32:35], v[24:27], v[28:31]
	s_nop 2
	ds_read_b128 v[28:31], v92 offset:32256
	s_waitcnt lgkmcnt(0)
	v_mfma_f32_16x16x32_bf16 v[20:23], v[28:31], v[20:23], v[24:27]
	s_nop 2
	ds_read_b128 v[24:27], v92 offset:32320
	s_waitcnt lgkmcnt(0)
	v_mfma_f32_16x16x32_bf16 v[16:19], v[24:27], v[16:19], v[20:23]
	s_nop 2
	v_mul_f32_e64 v22, v48, s24
	v_mul_f32_e64 v23, v49, s24
	v_pk_mul_f32 v[24:25], v[50:51], s[24:25] op_sel_hi:[1,0]
	v_mad_i64_i32 v[20:21], s[4:5], v84, s57, v[78:79]
	v_cvt_pk_bf16_f32 v22, v22, v23
	v_cvt_pk_bf16_f32 v23, v24, v25
	global_store_dwordx2 v[20:21], v[22:23], off
	v_pk_mul_f32 v[22:23], v[52:53], s[24:25] op_sel_hi:[1,0]
	v_pk_mul_f32 v[24:25], v[54:55], s[24:25] op_sel_hi:[1,0]
	v_cvt_pk_bf16_f32 v22, v22, v23
	v_cvt_pk_bf16_f32 v23, v24, v25
	global_store_dwordx2 v[20:21], v[22:23], off offset:32
	v_pk_mul_f32 v[22:23], v[56:57], s[24:25] op_sel_hi:[1,0]
	v_pk_mul_f32 v[24:25], v[58:59], s[24:25] op_sel_hi:[1,0]
	v_cvt_pk_bf16_f32 v22, v22, v23
	v_cvt_pk_bf16_f32 v23, v24, v25
	global_store_dwordx2 v[20:21], v[22:23], off offset:64
	v_pk_mul_f32 v[22:23], v[60:61], s[24:25] op_sel_hi:[1,0]
	v_pk_mul_f32 v[24:25], v[62:63], s[24:25] op_sel_hi:[1,0]
	v_cvt_pk_bf16_f32 v22, v22, v23
	v_cvt_pk_bf16_f32 v23, v24, v25
	global_store_dwordx2 v[20:21], v[22:23], off offset:96
	s_waitcnt vmcnt(4)
	v_mov_b32_e32 v22, v44
	v_mov_b32_e32 v23, v46
	v_mov_b32_e32 v46, v45
	v_mov_b32_e32 v26, v40
	v_mov_b32_e32 v27, v42
	v_mov_b32_e32 v42, v41
	v_pk_mul_f32 v[24:25], v[46:47], v[16:17]
	v_pk_mul_f32 v[28:29], v[42:43], v[18:19]
	v_pk_mul_f32 v[16:17], v[22:23], v[16:17]
	v_pk_mul_f32 v[18:19], v[26:27], v[18:19]
	v_pk_fma_f32 v[24:25], v[22:23], v[64:65], v[24:25] neg_lo:[0,0,1] neg_hi:[0,0,1]
	v_pk_fma_f32 v[28:29], v[26:27], v[66:67], v[28:29] neg_lo:[0,0,1] neg_hi:[0,0,1]
	v_pk_fma_f32 v[16:17], v[46:47], v[64:65], v[16:17]
	v_pk_fma_f32 v[18:19], v[42:43], v[66:67], v[18:19]
	v_pk_mul_f32 v[24:25], v[24:25], s[24:25] op_sel_hi:[1,0]
	v_pk_mul_f32 v[28:29], v[28:29], s[24:25] op_sel_hi:[1,0]
	v_pk_mul_f32 v[16:17], v[16:17], s[24:25] op_sel_hi:[1,0]
	v_pk_mul_f32 v[18:19], v[18:19], s[24:25] op_sel_hi:[1,0]
	v_cvt_pk_bf16_f32 v24, v24, v25
	v_cvt_pk_bf16_f32 v25, v28, v29
	v_cvt_pk_bf16_f32 v16, v16, v17
	v_cvt_pk_bf16_f32 v17, v18, v19
	global_store_dwordx2 v[20:21], v[24:25], off offset:128
	global_store_dwordx2 v[20:21], v[16:17], off offset:160
	v_add_u32_e32 v44, v88, v89
	ds_read_b128 v[16:19], v44 offset:38400
	ds_read_b128 v[20:23], v44 offset:38464
	s_waitcnt lgkmcnt(0)
	v_mfma_f32_16x16x32_bf16 v[16:19], v[16:19], v[12:15], 0
	ds_read_b128 v[24:27], v44 offset:43072
	ds_read_b128 v[28:31], v44 offset:47680
	ds_read_b128 v[36:39], v44 offset:56896
	v_mfma_f32_16x16x32_bf16 v[16:19], v[20:23], v[8:11], v[16:19]
	ds_read_b128 v[20:23], v44 offset:38528
	ds_read_b128 v[40:43], v44 offset:61504
	ds_read_b128 v[32:35], v94 offset:38464
	s_waitcnt lgkmcnt(0)
	v_mfma_f32_16x16x32_bf16 v[16:19], v[20:23], v[0:3], v[16:19]
	ds_read_b128 v[20:23], v44 offset:38592
	s_waitcnt lgkmcnt(0)
	v_mfma_f32_16x16x32_bf16 v[16:19], v[20:23], v[4:7], v[16:19]
	ds_read_b128 v[20:23], v44 offset:43008
	s_waitcnt lgkmcnt(0)
; __device__ __forceinline__ unsigned cvt_pk_bf16(float lo, float hi) { typedef float f2 __attribute__((ext_vector_type(2))); typedef __bf16 b2 __attribute__((ext_vector_type(2))); f2 v = {lo, hi}; b2 b = __builtin_convertvector(v, b2); return __builtin_bit_cast(unsigned, b); }
; #define MFMA16(a, b, c) __builtin_amdgcn_mfma_f32_16x16x32_bf16((a), (b), (c), 0, 0, 0)
; __device__ __forceinline__ void pp_mla_lds(int tok0, int hh, const bf16_t* PROJ, bf16_t* QC, bf16_t* KC, bf16_t* VC, const float2* rope, const char* Lq, const char* Lkv, const float* cqn, const float* ckvn, int lane) {
;     ...
;             for (int nt = 0; nt < 8; ++nt) { acc[nt] = (f32x4){0.f, 0.f, 0.f, 0.f}; const char* wr_ = Lkv + (nt * 16 + m) * 288 + quad * 16;
; #pragma unroll
;                 for (int ks = 0; ks < 4; ++ks) acc[nt] = MFMA16(*(const bf16x8*)(wr_ + ks * 64), ak[ks], acc[nt]); }
;             bf16_t* ko = KC + (size_t)tok * 384 + hh * 96 + quad * 4; bf16_t* vo = VC + (size_t)tok * 256 + hh * 64 + quad * 4;
; #pragma unroll
;             for (int nt = 0; nt < 4; ++nt) { u32x2 w; w.x = cvt_pk_bf16(acc[nt][0], acc[nt][1]); w.y = cvt_pk_bf16(acc[nt][2], acc[nt][3]); *(u32x2*)(ko + nt * 16) = w;
;                 u32x2 w2; w2.x = cvt_pk_bf16(acc[nt + 4][0], acc[nt + 4][1]); w2.y = cvt_pk_bf16(acc[nt + 4][2], acc[nt + 4][3]); *(u32x2*)(vo + nt * 16) = w2; } }
	v_mfma_f32_16x16x32_bf16 v[20:23], v[20:23], v[12:15], 0
	v_mfma_f32_16x16x32_bf16 v[20:23], v[24:27], v[8:11], v[20:23]
	ds_read_b128 v[24:27], v44 offset:43136
	s_waitcnt lgkmcnt(0)
	v_mfma_f32_16x16x32_bf16 v[20:23], v[24:27], v[0:3], v[20:23]
	ds_read_b128 v[24:27], v44 offset:43200
	s_waitcnt lgkmcnt(0)
	v_mfma_f32_16x16x32_bf16 v[20:23], v[24:27], v[4:7], v[20:23]
	ds_read_b128 v[24:27], v44 offset:47616
	s_waitcnt lgkmcnt(0)
	v_mfma_f32_16x16x32_bf16 v[24:27], v[24:27], v[12:15], 0
	v_mfma_f32_16x16x32_bf16 v[24:27], v[28:31], v[8:11], v[24:27]
	ds_read_b128 v[28:31], v44 offset:47744
	s_waitcnt lgkmcnt(0)
	v_mfma_f32_16x16x32_bf16 v[24:27], v[28:31], v[0:3], v[24:27]
	ds_read_b128 v[28:31], v44 offset:47808
	s_waitcnt lgkmcnt(0)
	v_mfma_f32_16x16x32_bf16 v[24:27], v[28:31], v[4:7], v[24:27]
	ds_read_b128 v[28:31], v94 offset:38400
	s_waitcnt lgkmcnt(0)
	v_mfma_f32_16x16x32_bf16 v[28:31], v[28:31], v[12:15], 0
	v_mfma_f32_16x16x32_bf16 v[28:31], v[32:35], v[8:11], v[28:31]
	ds_read_b128 v[32:35], v94 offset:38528
	s_waitcnt lgkmcnt(0)
	v_mfma_f32_16x16x32_bf16 v[28:31], v[32:35], v[0:3], v[28:31]
	ds_read_b128 v[32:35], v94 offset:38592
	s_waitcnt lgkmcnt(0)
	v_mfma_f32_16x16x32_bf16 v[28:31], v[32:35], v[4:7], v[28:31]
	ds_read_b128 v[32:35], v44 offset:56832
	s_waitcnt lgkmcnt(0)
	v_mfma_f32_16x16x32_bf16 v[32:35], v[32:35], v[12:15], 0
	v_mfma_f32_16x16x32_bf16 v[32:35], v[36:39], v[8:11], v[32:35]
	ds_read_b128 v[36:39], v44 offset:56960
	s_waitcnt lgkmcnt(0)
	v_mfma_f32_16x16x32_bf16 v[32:35], v[36:39], v[0:3], v[32:35]
	ds_read_b128 v[36:39], v44 offset:57024
	s_waitcnt lgkmcnt(0)
	v_mfma_f32_16x16x32_bf16 v[32:35], v[36:39], v[4:7], v[32:35]
	ds_read_b128 v[36:39], v44 offset:61440
	s_waitcnt lgkmcnt(0)
	v_mfma_f32_16x16x32_bf16 v[36:39], v[36:39], v[12:15], 0
	v_mfma_f32_16x16x32_bf16 v[36:39], v[40:43], v[8:11], v[36:39]
	ds_read_b128 v[40:43], v44 offset:61568
	s_waitcnt lgkmcnt(0)
	v_mfma_f32_16x16x32_bf16 v[36:39], v[40:43], v[0:3], v[36:39]
	ds_read_b128 v[40:43], v44 offset:61632
	ds_read_b128 v[44:47], v90 offset:27712
	s_waitcnt lgkmcnt(0)
	v_mfma_f32_16x16x32_bf16 v[36:39], v[40:43], v[4:7], v[36:39]
	ds_read_b128 v[40:43], v90 offset:27648
	s_waitcnt lgkmcnt(0)
	v_mfma_f32_16x16x32_bf16 v[40:43], v[40:43], v[12:15], 0
	v_mfma_f32_16x16x32_bf16 v[40:43], v[44:47], v[8:11], v[40:43]
	ds_read_b128 v[44:47], v90 offset:27776
	s_waitcnt lgkmcnt(0)
	v_mfma_f32_16x16x32_bf16 v[40:43], v[44:47], v[0:3], v[40:43]
	ds_read_b128 v[44:47], v90 offset:27840
	s_waitcnt lgkmcnt(0)
	v_mfma_f32_16x16x32_bf16 v[40:43], v[44:47], v[4:7], v[40:43]
	ds_read_b128 v[44:47], v95 offset:38400
	s_waitcnt lgkmcnt(0)
	v_mfma_f32_16x16x32_bf16 v[12:15], v[44:47], v[12:15], 0
	ds_read_b128 v[44:47], v95 offset:38464
	s_waitcnt lgkmcnt(0)
	v_mfma_f32_16x16x32_bf16 v[8:11], v[44:47], v[8:11], v[12:15]
	s_nop 4
	ds_read_b128 v[12:15], v95 offset:38528
	s_waitcnt lgkmcnt(0)
	v_mfma_f32_16x16x32_bf16 v[0:3], v[12:15], v[0:3], v[8:11]
	s_nop 2
	ds_read_b128 v[8:11], v95 offset:38592
	s_waitcnt lgkmcnt(0)
	v_mfma_f32_16x16x32_bf16 v[0:3], v[8:11], v[4:7], v[0:3]
	v_mad_i64_i32 v[4:5], s[4:5], v84, s57, v[80:81]
	v_lshlrev_b64 v[6:7], 9, v[84:85]
	v_cvt_pk_bf16_f32 v8, v16, v17
	v_cvt_pk_bf16_f32 v9, v18, v19
	v_lshl_add_u64 v[6:7], v[82:83], 0, v[6:7]
	global_store_dwordx2 v[4:5], v[8:9], off
	v_cvt_pk_bf16_f32 v8, v32, v33
	v_cvt_pk_bf16_f32 v9, v34, v35
	global_store_dwordx2 v[6:7], v[8:9], off
	v_cvt_pk_bf16_f32 v8, v20, v21
	v_cvt_pk_bf16_f32 v9, v22, v23
	global_store_dwordx2 v[4:5], v[8:9], off offset:32
	v_cvt_pk_bf16_f32 v8, v36, v37
	v_cvt_pk_bf16_f32 v9, v38, v39
	global_store_dwordx2 v[6:7], v[8:9], off offset:32
	v_cvt_pk_bf16_f32 v8, v24, v25
	v_cvt_pk_bf16_f32 v9, v26, v27
	global_store_dwordx2 v[4:5], v[8:9], off offset:64
	v_cvt_pk_bf16_f32 v8, v40, v41
	v_cvt_pk_bf16_f32 v9, v42, v43
	global_store_dwordx2 v[6:7], v[8:9], off offset:64
	v_cvt_pk_bf16_f32 v8, v28, v29
	v_cvt_pk_bf16_f32 v9, v30, v31
	v_cvt_pk_bf16_f32 v0, v0, v1
	v_cvt_pk_bf16_f32 v1, v2, v3
	v_add_u32_e32 v84, s58, v84
	global_store_dwordx2 v[4:5], v[8:9], off offset:96
	global_store_dwordx2 v[6:7], v[0:1], off offset:96
	s_cbranch_scc0 .LBB0_500
	s_branch .LBB0_443

; template <int DQK, int NSUB, int MODE>
; __device__ __forceinline__ void flash_unit(LAS char* L, const bf16_t* Qp, int qpitch, const bf16_t* Kp, int kpitch, const bf16_t* Vp, int vpitch,
;                                            bf16_t* Op, int opitch, float lam, float oscale, const float* subln) {
;     ...
;     for (int t = 0; t < SEQ / 64; ++t) {
;         const int buf = t & 1;
;         if (t + 1 < SEQ / 64) { const size_t ko = (size_t)(t + 1) * 64 * kpitch, vo = (size_t)(t + 1) * 64 * vpitch;
;             rk1 = *(const u32x4*)(kg1 + ko); if (has2) rk2 = *(const u32x4*)(kg2 + ko); rv1 = *(const u32x4*)(vg1 + vo); }
;         const char* Kb = Lg + buf * KBUF; LAS const char* Vb = L + OFF_V + buf * VBUF + voff;
; #pragma unroll
;         for (int s = 0; s < NSUB; ++s) {
;             f32x16 p0, p1;
; #pragma unroll
;             for (int d0 = 0; d0 < ND0; ++d0) { const bf16x8 k0 = *(const bf16x8*)(Kb + r32 * KPB + (s * DQK + 16 * d0 + 8 * hi) * 2); const bf16x8 k1 = *(const bf16x8*)(Kb + (32 + r32) * KPB + (s * DQK + 16 * d0 + 8 * hi) * 2);
;                 if (d0 == 0) { p0 = MFMA32(k0, qf[s][d0], negm[s]); p1 = MFMA32(k1, qf[s][d0], negm[s]); }
;                 else { p0 = MFMA32(k0, qf[s][d0], p0); p1 = MFMA32(k1, qf[s][d0], p1); } }
; #pragma unroll
;             for (int hf = 0; hf < 2; ++hf) {
;                 f32x16& ph = hf ? p1 : p0;
;                 float mx = fmaxf(ph[0], ph[1]);
; #pragma unroll
;                 for (int r = 2; r < 16; ++r) mx = fmaxf(mx, ph[r]);
;                 mx = fmaxf(mx, __shfl_xor(mx, 32));
;                 const bool first = (t == 0) && (hf == 0);
;                 if (first || __any(mx > 8.0f)) {
;                     const float dl = first ? mx : fmaxf(mx, 0.f); mref[s] += dl;
; #pragma unroll
;                     for (int r = 0; r < 16; ++r) { ph[r] -= dl; negm[s][r] = -mref[s]; }
;                     if (hf == 0) {
; #pragma unroll
;                         for (int r = 0; r < 16; ++r) p1[r] -= dl;
;                     }
;                     if (!first) { const float alpha = __builtin_amdgcn_exp2f(-dl); lrow[s] *= alpha;
; #pragma unroll
;                         for (int r = 0; r < 16; ++r) { o[s][0][r] *= alpha; o[s][1][r] *= alpha; } }
;                 }
; #pragma unroll
;                 for (int r = 0; r < 16; ++r) ph[r] = __builtin_amdgcn_exp2f(ph[r]);
.LBB0_579:
	s_and_b32 s8, s22, 1
	s_mul_i32 s9, s8, 0x2400
	v_add_u32_e32 v195, s9, v192
	v_add_u32_e32 v229, s9, v191
	ds_read_b128 v[96:99], v195
	ds_read_b128 v[100:103], v195 offset:32
	ds_read_b128 v[170:173], v195 offset:4608
	ds_read_b128 v[174:177], v195 offset:4640
	ds_read_b64_tr_b16 v[204:205], v229 offset:18432
	ds_read_b64_tr_b16 v[206:207], v229 offset:19584
	ds_read_b64_tr_b16 v[208:209], v229 offset:20736
	ds_read_b64_tr_b16 v[210:211], v229 offset:21888
	ds_read_b64_tr_b16 v[212:213], v229 offset:18496
	ds_read_b64_tr_b16 v[214:215], v229 offset:19648
	ds_read_b64_tr_b16 v[216:217], v229 offset:20800
	ds_read_b64_tr_b16 v[218:219], v229 offset:21952
	s_waitcnt lgkmcnt(8)
	v_mfma_f32_32x32x16_bf16 v[112:127], v[96:99], v[128:131], v[32:47]
	v_mfma_f32_32x32x16_bf16 v[112:127], v[100:103], v[132:135], v[112:127]
	s_nop 11
	v_max_f32_e32 v158, v113, v113
	v_max_f32_e32 v169, v112, v112
	v_mfma_f32_32x32x16_bf16 v[96:111], v[170:173], v[128:131], v[32:47]
	v_max_f32_e32 v158, v169, v158
	v_max3_f32 v158, v158, v114, v115
	v_max3_f32 v158, v158, v116, v117
	v_max3_f32 v158, v158, v118, v119
	v_max3_f32 v158, v158, v120, v121
	v_max3_f32 v158, v158, v122, v123
	v_max3_f32 v158, v158, v124, v125
	v_max3_f32 v158, v158, v126, v127
	v_mfma_f32_32x32x16_bf16 v[96:111], v[174:177], v[132:135], v[96:111]
	v_cmp_lt_f32_e32 vcc, s61, v158
	s_cbranch_vccz .LBB0_581
	ds_bpermute_b32 v169, v184, v158
	s_waitcnt lgkmcnt(0)
	v_max_f32_e32 v169, v169, v169
	v_max_f32_e32 v158, v158, v169
	v_max_f32_e32 v32, v158, v158
	v_max_f32_e32 v34, 0, v32
	v_exp_f32_e64 v36, -v34
	v_add_f32_e32 v159, v159, v34
	v_xor_b32_e32 v32, 0x80000000, v159
	v_pk_add_f32 v[112:113], v[112:113], v[34:35] op_sel_hi:[1,0] neg_lo:[0,1] neg_hi:[0,1]
	v_pk_add_f32 v[114:115], v[114:115], v[34:35] op_sel_hi:[1,0] neg_lo:[0,1] neg_hi:[0,1]
	v_pk_add_f32 v[116:117], v[116:117], v[34:35] op_sel_hi:[1,0] neg_lo:[0,1] neg_hi:[0,1]
	v_pk_add_f32 v[118:119], v[118:119], v[34:35] op_sel_hi:[1,0] neg_lo:[0,1] neg_hi:[0,1]
	v_pk_add_f32 v[120:121], v[120:121], v[34:35] op_sel_hi:[1,0] neg_lo:[0,1] neg_hi:[0,1]
	v_pk_add_f32 v[122:123], v[122:123], v[34:35] op_sel_hi:[1,0] neg_lo:[0,1] neg_hi:[0,1]
	v_pk_add_f32 v[124:125], v[124:125], v[34:35] op_sel_hi:[1,0] neg_lo:[0,1] neg_hi:[0,1]
	v_pk_add_f32 v[126:127], v[126:127], v[34:35] op_sel_hi:[1,0] neg_lo:[0,1] neg_hi:[0,1]
	v_sub_f32_e32 v111, v111, v34
	v_sub_f32_e32 v110, v110, v34
	v_sub_f32_e32 v109, v109, v34
	v_sub_f32_e32 v108, v108, v34
	v_sub_f32_e32 v107, v107, v34
	v_sub_f32_e32 v106, v106, v34
	v_sub_f32_e32 v105, v105, v34
	v_sub_f32_e32 v104, v104, v34
	v_sub_f32_e32 v103, v103, v34
	v_sub_f32_e32 v102, v102, v34
	v_sub_f32_e32 v101, v101, v34
	v_sub_f32_e32 v100, v100, v34
	v_sub_f32_e32 v99, v99, v34
	v_sub_f32_e32 v98, v98, v34
	v_sub_f32_e32 v97, v97, v34
	v_sub_f32_e32 v96, v96, v34
	v_pk_mul_f32 v[14:15], v[14:15], v[36:37] op_sel_hi:[1,0]
	v_pk_mul_f32 v[12:13], v[12:13], v[36:37] op_sel_hi:[1,0]
	v_pk_mul_f32 v[10:11], v[10:11], v[36:37] op_sel_hi:[1,0]
	v_pk_mul_f32 v[8:9], v[8:9], v[36:37] op_sel_hi:[1,0]
	v_pk_mul_f32 v[6:7], v[6:7], v[36:37] op_sel_hi:[1,0]
	v_pk_mul_f32 v[4:5], v[4:5], v[36:37] op_sel_hi:[1,0]
	v_pk_mul_f32 v[2:3], v[2:3], v[36:37] op_sel_hi:[1,0]
	v_pk_mul_f32 v[0:1], v[0:1], v[36:37] op_sel_hi:[1,0]
	v_pk_mul_f32 v[30:31], v[30:31], v[36:37] op_sel_hi:[1,0]
	v_pk_mul_f32 v[28:29], v[28:29], v[36:37] op_sel_hi:[1,0]
	v_pk_mul_f32 v[26:27], v[26:27], v[36:37] op_sel_hi:[1,0]
	v_pk_mul_f32 v[24:25], v[24:25], v[36:37] op_sel_hi:[1,0]
	v_pk_mul_f32 v[22:23], v[22:23], v[36:37] op_sel_hi:[1,0]
	v_pk_mul_f32 v[20:21], v[20:21], v[36:37] op_sel_hi:[1,0]
	v_pk_mul_f32 v[18:19], v[18:19], v[36:37] op_sel_hi:[1,0]
	v_pk_mul_f32 v[16:17], v[16:17], v[36:37] op_sel_hi:[1,0]
	v_mul_f32_e32 v168, v168, v36
	v_mov_b32_e32 v33, v32
	v_mov_b32_e32 v34, v32
	v_mov_b32_e32 v35, v32
	v_mov_b32_e32 v36, v32
	v_mov_b32_e32 v37, v32
	v_mov_b32_e32 v38, v32
	v_mov_b32_e32 v39, v32
	v_mov_b32_e32 v40, v32
	v_mov_b32_e32 v41, v32
	v_mov_b32_e32 v42, v32
	v_mov_b32_e32 v43, v32
	v_mov_b32_e32 v44, v32
	v_mov_b32_e32 v45, v32
	v_mov_b32_e32 v46, v32
	v_mov_b32_e32 v47, v32
.LBB0_581:
	v_exp_f32_e32 v112, v112
	v_exp_f32_e32 v113, v113
	v_exp_f32_e32 v114, v114
	v_exp_f32_e32 v115, v115
	v_exp_f32_e32 v116, v116
	v_exp_f32_e32 v117, v117
	v_exp_f32_e32 v118, v118
	v_exp_f32_e32 v119, v119
	v_exp_f32_e32 v120, v120
	v_exp_f32_e32 v121, v121
	v_exp_f32_e32 v122, v122
	v_exp_f32_e32 v123, v123
	v_pk_add_f32 v[170:171], v[112:113], v[114:115]
	v_add_u32_e32 v158, s9, v191
	v_pk_add_f32 v[170:171], v[116:117], v[170:171]
	v_cvt_pk_bf16_f32 v112, v112, v113
	v_pk_add_f32 v[170:171], v[118:119], v[170:171]
	v_cvt_pk_bf16_f32 v113, v114, v115
	v_pk_add_f32 v[170:171], v[120:121], v[170:171]
	v_cvt_pk_bf16_f32 v114, v116, v117
	v_pk_add_f32 v[170:171], v[122:123], v[170:171]
	v_cvt_pk_bf16_f32 v116, v120, v121
	v_cvt_pk_bf16_f32 v117, v122, v123
	ds_read_b64_tr_b16 v[220:221], v158 offset:23040
	ds_read_b64_tr_b16 v[222:223], v158 offset:24192
	v_cvt_pk_bf16_f32 v115, v118, v119
	v_exp_f32_e32 v124, v124
	v_exp_f32_e32 v125, v125
	s_waitcnt lgkmcnt(8)
	v_mfma_f32_32x32x16_bf16 v[0:15], v[204:207], v[112:115], v[0:15]
	v_exp_f32_e32 v126, v126
	v_exp_f32_e32 v127, v127
	ds_read_b64_tr_b16 v[224:225], v158 offset:25344
	ds_read_b64_tr_b16 v[226:227], v158 offset:26496
	v_cvt_pk_bf16_f32 v118, v124, v125
	v_pk_add_f32 v[170:171], v[124:125], v[170:171]
	v_cvt_pk_bf16_f32 v119, v126, v127
	v_pk_add_f32 v[170:171], v[126:127], v[170:171]
	s_waitcnt lgkmcnt(8)
	v_mfma_f32_32x32x16_bf16 v[0:15], v[208:211], v[116:119], v[0:15]
	ds_read_b64_tr_b16 v[236:237], v158 offset:23104
	ds_read_b64_tr_b16 v[238:239], v158 offset:24256
	v_add_f32_e32 v169, v170, v171
	v_add_f32_e32 v194, v168, v169
	s_waitcnt lgkmcnt(8)
	v_mfma_f32_32x32x16_bf16 v[16:31], v[212:215], v[112:115], v[16:31]
	s_waitcnt lgkmcnt(6)
	v_mfma_f32_32x32x16_bf16 v[16:31], v[216:219], v[116:119], v[16:31]
	v_max_f32_e32 v112, v97, v97
	v_max_f32_e32 v113, v96, v96
	v_max_f32_e32 v112, v113, v112
	v_max3_f32 v112, v112, v98, v99
	v_max3_f32 v112, v112, v100, v101
	v_max3_f32 v112, v112, v102, v103
	v_max3_f32 v112, v112, v104, v105
	v_max3_f32 v112, v112, v106, v107
	v_max3_f32 v112, v112, v108, v109
	v_max3_f32 v112, v112, v110, v111
	v_cmp_lt_f32_e32 vcc, s61, v112
	s_cbranch_vccz .LBB0_583
; __device__ __forceinline__ unsigned cvt_pk_bf16(float lo, float hi) { typedef float f2 __attribute__((ext_vector_type(2))); typedef __bf16 b2 __attribute__((ext_vector_type(2))); f2 v = {lo, hi}; b2 b = __builtin_convertvector(v, b2); return __builtin_bit_cast(unsigned, b); }
; __device__ __forceinline__ v4i16_t vtr(LAS const char* p) { return __builtin_amdgcn_ds_read_tr16_b64_v4i16((LAS v4i16_t*)p); }
; template <int DQK, int NSUB, int MODE>
; __device__ __forceinline__ void flash_unit(LAS char* L, const bf16_t* Qp, int qpitch, const bf16_t* Kp, int kpitch, const bf16_t* Vp, int vpitch,
;                                            bf16_t* Op, int opitch, float lam, float oscale, const float* subln) {
;     ...
;         for (int s = 0; s < NSUB; ++s) {
;             f32x16 p0, p1;
; #pragma unroll
;             for (int d0 = 0; d0 < ND0; ++d0) { const bf16x8 k0 = *(const bf16x8*)(Kb + r32 * KPB + (s * DQK + 16 * d0 + 8 * hi) * 2); const bf16x8 k1 = *(const bf16x8*)(Kb + (32 + r32) * KPB + (s * DQK + 16 * d0 + 8 * hi) * 2);
;                 if (d0 == 0) { p0 = MFMA32(k0, qf[s][d0], negm[s]); p1 = MFMA32(k1, qf[s][d0], negm[s]); }
;                 else { p0 = MFMA32(k0, qf[s][d0], p0); p1 = MFMA32(k1, qf[s][d0], p1); } }
;     ...
;                 for (int r = 0; r < 16; ++r) ph[r] = __builtin_amdgcn_exp2f(ph[r]);
;                 { typedef float f32x2_ __attribute__((ext_vector_type(2))); f32x2_ r2 = {ph[0], ph[1]};
; #pragma unroll
;                   for (int r = 2; r < 16; r += 2) r2 += (f32x2_){ph[r], ph[r + 1]};
;                   lrow[s] += r2[0] + r2[1]; }
;                 bf16x8 pf[2];
; #pragma unroll
;                 for (int k2 = 0; k2 < 2; ++k2) { u32x4 w;
; #pragma unroll
;                     for (int e = 0; e < 4; ++e) w[e] = cvt_pk_bf16(ph[8 * k2 + 2 * e], ph[8 * k2 + 2 * e + 1]);
;                     pf[k2] = __builtin_bit_cast(bf16x8, w); }
; #pragma unroll
;                 for (int db = 0; db < 2; ++db)
; #pragma unroll
;                     for (int k2 = 0; k2 < 2; ++k2) { const int ks = 2 * hf + k2; const v4i16_t lo = vtr(Vb + (16 * ks) * VPB + db * 64), hh = vtr(Vb + (16 * ks + 8) * VPB + db * 64);
;                         const bf16x8 vf = {lo[0], lo[1], lo[2], lo[3], hh[0], hh[1], hh[2], hh[3]};
;                         o[s][db] = MFMA32(vf, pf[k2], o[s][db]); }
	ds_bpermute_b32 v113, v184, v112
	s_waitcnt lgkmcnt(0)
	v_max_f32_e32 v113, v113, v113
	v_max_f32_e32 v112, v112, v113
	v_max_f32_e32 v32, v112, v112
	v_max_f32_e32 v34, 0, v32
	v_exp_f32_e64 v36, -v34
	v_add_f32_e32 v159, v159, v34
	v_xor_b32_e32 v32, 0x80000000, v159
	v_pk_add_f32 v[96:97], v[96:97], v[34:35] op_sel_hi:[1,0] neg_lo:[0,1] neg_hi:[0,1]
	v_pk_add_f32 v[98:99], v[98:99], v[34:35] op_sel_hi:[1,0] neg_lo:[0,1] neg_hi:[0,1]
	v_pk_add_f32 v[100:101], v[100:101], v[34:35] op_sel_hi:[1,0] neg_lo:[0,1] neg_hi:[0,1]
	v_pk_add_f32 v[102:103], v[102:103], v[34:35] op_sel_hi:[1,0] neg_lo:[0,1] neg_hi:[0,1]
	v_pk_add_f32 v[104:105], v[104:105], v[34:35] op_sel_hi:[1,0] neg_lo:[0,1] neg_hi:[0,1]
	v_pk_add_f32 v[106:107], v[106:107], v[34:35] op_sel_hi:[1,0] neg_lo:[0,1] neg_hi:[0,1]
	v_pk_add_f32 v[108:109], v[108:109], v[34:35] op_sel_hi:[1,0] neg_lo:[0,1] neg_hi:[0,1]
	v_pk_add_f32 v[110:111], v[110:111], v[34:35] op_sel_hi:[1,0] neg_lo:[0,1] neg_hi:[0,1]
	v_pk_mul_f32 v[14:15], v[14:15], v[36:37] op_sel_hi:[1,0]
	v_pk_mul_f32 v[12:13], v[12:13], v[36:37] op_sel_hi:[1,0]
	v_pk_mul_f32 v[10:11], v[10:11], v[36:37] op_sel_hi:[1,0]
	v_pk_mul_f32 v[8:9], v[8:9], v[36:37] op_sel_hi:[1,0]
	v_pk_mul_f32 v[6:7], v[6:7], v[36:37] op_sel_hi:[1,0]
	v_pk_mul_f32 v[4:5], v[4:5], v[36:37] op_sel_hi:[1,0]
	v_pk_mul_f32 v[2:3], v[2:3], v[36:37] op_sel_hi:[1,0]
	v_pk_mul_f32 v[0:1], v[0:1], v[36:37] op_sel_hi:[1,0]
	v_pk_mul_f32 v[30:31], v[30:31], v[36:37] op_sel_hi:[1,0]
	v_pk_mul_f32 v[28:29], v[28:29], v[36:37] op_sel_hi:[1,0]
	v_pk_mul_f32 v[26:27], v[26:27], v[36:37] op_sel_hi:[1,0]
	v_pk_mul_f32 v[24:25], v[24:25], v[36:37] op_sel_hi:[1,0]
	v_pk_mul_f32 v[22:23], v[22:23], v[36:37] op_sel_hi:[1,0]
	v_pk_mul_f32 v[20:21], v[20:21], v[36:37] op_sel_hi:[1,0]
	v_pk_mul_f32 v[18:19], v[18:19], v[36:37] op_sel_hi:[1,0]
	v_pk_mul_f32 v[16:17], v[16:17], v[36:37] op_sel_hi:[1,0]
	v_mul_f32_e32 v194, v194, v36
	v_mov_b32_e32 v33, v32
	v_mov_b32_e32 v34, v32
	v_mov_b32_e32 v35, v32
	v_mov_b32_e32 v36, v32
	v_mov_b32_e32 v37, v32
	v_mov_b32_e32 v38, v32
	v_mov_b32_e32 v39, v32
	v_mov_b32_e32 v40, v32
	v_mov_b32_e32 v41, v32
	v_mov_b32_e32 v42, v32
	v_mov_b32_e32 v43, v32
	v_mov_b32_e32 v44, v32
	v_mov_b32_e32 v45, v32
	v_mov_b32_e32 v46, v32
	v_mov_b32_e32 v47, v32
.LBB0_583:
	v_exp_f32_e32 v168, v96
	v_exp_f32_e32 v169, v97
	v_exp_f32_e32 v170, v98
	v_exp_f32_e32 v171, v99
	v_exp_f32_e32 v172, v100
	v_exp_f32_e32 v173, v101
	v_exp_f32_e32 v174, v102
	v_exp_f32_e32 v175, v103
	v_exp_f32_e32 v176, v104
	v_exp_f32_e32 v177, v105
	v_exp_f32_e32 v178, v106
	v_exp_f32_e32 v179, v107
	v_cvt_pk_bf16_f32 v96, v168, v169
	v_cvt_pk_bf16_f32 v97, v170, v171
	v_cvt_pk_bf16_f32 v98, v172, v173
	v_cvt_pk_bf16_f32 v99, v174, v175
	v_exp_f32_e32 v180, v108
	v_exp_f32_e32 v181, v109
	s_waitcnt lgkmcnt(0)
	v_mfma_f32_32x32x16_bf16 v[0:15], v[220:223], v[96:99], v[0:15]
	v_exp_f32_e32 v182, v110
	v_exp_f32_e32 v183, v111
	v_cvt_pk_bf16_f32 v100, v176, v177
	v_cvt_pk_bf16_f32 v101, v178, v179
	v_cvt_pk_bf16_f32 v102, v180, v181
	v_cvt_pk_bf16_f32 v103, v182, v183
	s_waitcnt lgkmcnt(0)
	s_nop 0
	v_mfma_f32_32x32x16_bf16 v[0:15], v[224:227], v[100:103], v[0:15]
	s_waitcnt lgkmcnt(0)
	v_mfma_f32_32x32x16_bf16 v[16:31], v[236:239], v[96:99], v[16:31]
	ds_read_b64_tr_b16 v[96:97], v158 offset:25408
	ds_read_b64_tr_b16 v[98:99], v158 offset:26560
	s_waitcnt lgkmcnt(0)
	v_mfma_f32_32x32x16_bf16 v[16:31], v[96:99], v[100:103], v[16:31]
	ds_read_b128 v[196:199], v195 offset:4672
	ds_read_b128 v[96:99], v195 offset:64
	ds_read_b128 v[200:203], v195 offset:96
	s_waitcnt lgkmcnt(0)
	v_mfma_f32_32x32x16_bf16 v[112:127], v[96:99], v[136:139], v[80:95]
	v_mfma_f32_32x32x16_bf16 v[112:127], v[200:203], v[140:143], v[112:127]
	s_nop 0
	v_mfma_f32_32x32x16_bf16 v[96:111], v[196:199], v[136:139], v[80:95]
	ds_read_b128 v[196:199], v195 offset:4704
	s_nop 8
	v_max_f32_e32 v195, v113, v113
	s_waitcnt lgkmcnt(0)
	v_mfma_f32_32x32x16_bf16 v[96:111], v[196:199], v[140:143], v[96:111]
	ds_read_b64_tr_b16 v[200:201], v158 offset:25408
	ds_read_b64_tr_b16 v[202:203], v158 offset:26560
	v_max_f32_e32 v196, v112, v112
	v_max_f32_e32 v195, v196, v195
	v_max3_f32 v195, v195, v114, v115
	v_max3_f32 v195, v195, v116, v117
	v_max3_f32 v195, v195, v118, v119
	v_max3_f32 v195, v195, v120, v121
	v_max3_f32 v195, v195, v122, v123
	v_max3_f32 v195, v195, v124, v125
	v_max3_f32 v195, v195, v126, v127
	v_cmp_lt_f32_e32 vcc, s61, v195
	s_cbranch_vccz .LBB0_585
; template <int DQK, int NSUB, int MODE>
; __device__ __forceinline__ void flash_unit(LAS char* L, const bf16_t* Qp, int qpitch, const bf16_t* Kp, int kpitch, const bf16_t* Vp, int vpitch,
;                                            bf16_t* Op, int opitch, float lam, float oscale, const float* subln) {
;     ...
;                 if (first || __any(mx > 8.0f)) {
;                     const float dl = first ? mx : fmaxf(mx, 0.f); mref[s] += dl;
; #pragma unroll
;                     for (int r = 0; r < 16; ++r) { ph[r] -= dl; negm[s][r] = -mref[s]; }
;                     if (hf == 0) {
; #pragma unroll
;                         for (int r = 0; r < 16; ++r) p1[r] -= dl;
;                     }
;                     if (!first) { const float alpha = __builtin_amdgcn_exp2f(-dl); lrow[s] *= alpha;
; #pragma unroll
;                         for (int r = 0; r < 16; ++r) { o[s][0][r] *= alpha; o[s][1][r] *= alpha; } }
;                 }
	ds_bpermute_b32 v196, v184, v195
	s_waitcnt lgkmcnt(0)
	v_max_f32_e32 v196, v196, v196
	v_max_f32_e32 v195, v195, v196
	v_max_f32_e32 v80, v195, v195
	v_max_f32_e32 v82, 0, v80
	v_exp_f32_e64 v84, -v82
	v_add_f32_e32 v161, v161, v82
	v_xor_b32_e32 v80, 0x80000000, v161
	v_pk_add_f32 v[112:113], v[112:113], v[82:83] op_sel_hi:[1,0] neg_lo:[0,1] neg_hi:[0,1]
	v_pk_add_f32 v[114:115], v[114:115], v[82:83] op_sel_hi:[1,0] neg_lo:[0,1] neg_hi:[0,1]
	v_pk_add_f32 v[116:117], v[116:117], v[82:83] op_sel_hi:[1,0] neg_lo:[0,1] neg_hi:[0,1]
	v_pk_add_f32 v[118:119], v[118:119], v[82:83] op_sel_hi:[1,0] neg_lo:[0,1] neg_hi:[0,1]
	v_pk_add_f32 v[120:121], v[120:121], v[82:83] op_sel_hi:[1,0] neg_lo:[0,1] neg_hi:[0,1]
	v_pk_add_f32 v[122:123], v[122:123], v[82:83] op_sel_hi:[1,0] neg_lo:[0,1] neg_hi:[0,1]
	v_pk_add_f32 v[124:125], v[124:125], v[82:83] op_sel_hi:[1,0] neg_lo:[0,1] neg_hi:[0,1]
	v_pk_add_f32 v[126:127], v[126:127], v[82:83] op_sel_hi:[1,0] neg_lo:[0,1] neg_hi:[0,1]
	v_sub_f32_e32 v111, v111, v82
	v_sub_f32_e32 v110, v110, v82
	v_sub_f32_e32 v109, v109, v82
	v_sub_f32_e32 v108, v108, v82
	v_sub_f32_e32 v107, v107, v82
	v_sub_f32_e32 v106, v106, v82
	v_sub_f32_e32 v105, v105, v82
	v_sub_f32_e32 v104, v104, v82
	v_sub_f32_e32 v103, v103, v82
	v_sub_f32_e32 v102, v102, v82
	v_sub_f32_e32 v101, v101, v82
	v_sub_f32_e32 v100, v100, v82
	v_sub_f32_e32 v99, v99, v82
	v_sub_f32_e32 v98, v98, v82
	v_sub_f32_e32 v97, v97, v82
	v_sub_f32_e32 v96, v96, v82
	v_pk_mul_f32 v[62:63], v[62:63], v[84:85] op_sel_hi:[1,0]
	v_pk_mul_f32 v[60:61], v[60:61], v[84:85] op_sel_hi:[1,0]
	v_pk_mul_f32 v[58:59], v[58:59], v[84:85] op_sel_hi:[1,0]
	v_pk_mul_f32 v[56:57], v[56:57], v[84:85] op_sel_hi:[1,0]
	v_pk_mul_f32 v[54:55], v[54:55], v[84:85] op_sel_hi:[1,0]
	v_pk_mul_f32 v[52:53], v[52:53], v[84:85] op_sel_hi:[1,0]
	v_pk_mul_f32 v[50:51], v[50:51], v[84:85] op_sel_hi:[1,0]
	v_pk_mul_f32 v[48:49], v[48:49], v[84:85] op_sel_hi:[1,0]
	v_pk_mul_f32 v[78:79], v[78:79], v[84:85] op_sel_hi:[1,0]
	v_pk_mul_f32 v[76:77], v[76:77], v[84:85] op_sel_hi:[1,0]
	v_pk_mul_f32 v[74:75], v[74:75], v[84:85] op_sel_hi:[1,0]
	v_pk_mul_f32 v[72:73], v[72:73], v[84:85] op_sel_hi:[1,0]
	v_pk_mul_f32 v[70:71], v[70:71], v[84:85] op_sel_hi:[1,0]
	v_pk_mul_f32 v[68:69], v[68:69], v[84:85] op_sel_hi:[1,0]
	v_pk_mul_f32 v[66:67], v[66:67], v[84:85] op_sel_hi:[1,0]
	v_pk_mul_f32 v[64:65], v[64:65], v[84:85] op_sel_hi:[1,0]
	v_mul_f32_e32 v160, v160, v84
	v_mov_b32_e32 v81, v80
	v_mov_b32_e32 v82, v80
	v_mov_b32_e32 v83, v80
	v_mov_b32_e32 v84, v80
	v_mov_b32_e32 v85, v80
	v_mov_b32_e32 v86, v80
	v_mov_b32_e32 v87, v80
	v_mov_b32_e32 v88, v80
	v_mov_b32_e32 v89, v80
	v_mov_b32_e32 v90, v80
	v_mov_b32_e32 v91, v80
	v_mov_b32_e32 v92, v80
	v_mov_b32_e32 v93, v80
	v_mov_b32_e32 v94, v80
	v_mov_b32_e32 v95, v80
; __device__ __forceinline__ unsigned cvt_pk_bf16(float lo, float hi) { typedef float f2 __attribute__((ext_vector_type(2))); typedef __bf16 b2 __attribute__((ext_vector_type(2))); f2 v = {lo, hi}; b2 b = __builtin_convertvector(v, b2); return __builtin_bit_cast(unsigned, b); }
; __device__ __forceinline__ v4i16_t vtr(LAS const char* p) { return __builtin_amdgcn_ds_read_tr16_b64_v4i16((LAS v4i16_t*)p); }
; #define MFMA32(a, b, c) __builtin_amdgcn_mfma_f32_32x32x16_bf16((a), (b), (c), 0, 0, 0)
; template <int DQK, int NSUB, int MODE>
; __device__ __forceinline__ void flash_unit(LAS char* L, const bf16_t* Qp, int qpitch, const bf16_t* Kp, int kpitch, const bf16_t* Vp, int vpitch,
;                                            bf16_t* Op, int opitch, float lam, float oscale, const float* subln) {
;     ...
; #pragma unroll
;                 for (int r = 0; r < 16; ++r) ph[r] = __builtin_amdgcn_exp2f(ph[r]);
;                 { typedef float f32x2_ __attribute__((ext_vector_type(2))); f32x2_ r2 = {ph[0], ph[1]};
; #pragma unroll
;                   for (int r = 2; r < 16; r += 2) r2 += (f32x2_){ph[r], ph[r + 1]};
;                   lrow[s] += r2[0] + r2[1]; }
;                 bf16x8 pf[2];
; #pragma unroll
;                 for (int k2 = 0; k2 < 2; ++k2) { u32x4 w;
; #pragma unroll
;                     for (int e = 0; e < 4; ++e) w[e] = cvt_pk_bf16(ph[8 * k2 + 2 * e], ph[8 * k2 + 2 * e + 1]);
;                     pf[k2] = __builtin_bit_cast(bf16x8, w); }
; #pragma unroll
;                 for (int db = 0; db < 2; ++db)
; #pragma unroll
;                     for (int k2 = 0; k2 < 2; ++k2) { const int ks = 2 * hf + k2; const v4i16_t lo = vtr(Vb + (16 * ks) * VPB + db * 64), hh = vtr(Vb + (16 * ks + 8) * VPB + db * 64);
;                         const bf16x8 vf = {lo[0], lo[1], lo[2], lo[3], hh[0], hh[1], hh[2], hh[3]};
;                         o[s][db] = MFMA32(vf, pf[k2], o[s][db]); }
;             }
;         }
;         if (t + 1 < SEQ / 64) { char* Kn = Lg + (buf ^ 1) * KBUF; *(u32x4*)(Kn + kl1) = rk1; if (has2) *(u32x4*)(Kn + kl2) = rk2; *(u32x4*)(Lg + OFF_V + (buf ^ 1) * VBUF + vl1) = rv1; }
;         __syncthreads();
.LBB0_585:
	v_exp_f32_e32 v112, v112
	v_exp_f32_e32 v113, v113
	v_exp_f32_e32 v114, v114
	v_exp_f32_e32 v115, v115
	v_exp_f32_e32 v116, v116
	v_exp_f32_e32 v117, v117
	v_exp_f32_e32 v118, v118
	v_exp_f32_e32 v119, v119
	v_exp_f32_e32 v120, v120
	v_exp_f32_e32 v121, v121
	v_exp_f32_e32 v122, v122
	v_exp_f32_e32 v123, v123
	v_pk_add_f32 v[196:197], v[112:113], v[114:115]
	v_cvt_pk_bf16_f32 v112, v112, v113
	v_pk_add_f32 v[196:197], v[116:117], v[196:197]
	v_cvt_pk_bf16_f32 v113, v114, v115
	v_pk_add_f32 v[196:197], v[118:119], v[196:197]
	v_cvt_pk_bf16_f32 v114, v116, v117
	v_pk_add_f32 v[196:197], v[120:121], v[196:197]
	v_cvt_pk_bf16_f32 v116, v120, v121
	v_pk_add_f32 v[196:197], v[122:123], v[196:197]
	v_cvt_pk_bf16_f32 v117, v122, v123
	v_cvt_pk_bf16_f32 v115, v118, v119
	v_exp_f32_e32 v124, v124
	v_exp_f32_e32 v125, v125
	s_waitcnt lgkmcnt(0)
	v_mfma_f32_32x32x16_bf16 v[48:63], v[204:207], v[112:115], v[48:63]
	v_exp_f32_e32 v126, v126
	v_exp_f32_e32 v127, v127
	v_cvt_pk_bf16_f32 v118, v124, v125
	v_pk_add_f32 v[196:197], v[124:125], v[196:197]
	v_cvt_pk_bf16_f32 v119, v126, v127
	v_pk_add_f32 v[196:197], v[126:127], v[196:197]
	s_waitcnt lgkmcnt(0)
	v_mfma_f32_32x32x16_bf16 v[48:63], v[208:211], v[116:119], v[48:63]
	v_add_f32_e32 v195, v196, v197
	s_waitcnt lgkmcnt(0)
	v_mfma_f32_32x32x16_bf16 v[64:79], v[212:215], v[112:115], v[64:79]
	s_waitcnt lgkmcnt(0)
	v_mfma_f32_32x32x16_bf16 v[64:79], v[216:219], v[116:119], v[64:79]
	v_max_f32_e32 v113, v97, v97
	v_max_f32_e32 v114, v96, v96
	v_max_f32_e32 v113, v114, v113
	v_max3_f32 v113, v113, v98, v99
	v_max3_f32 v113, v113, v100, v101
	v_max3_f32 v113, v113, v102, v103
	v_max3_f32 v113, v113, v104, v105
	v_max3_f32 v113, v113, v106, v107
	v_max3_f32 v113, v113, v108, v109
	v_max3_f32 v113, v113, v110, v111
	v_add_f32_e32 v112, v160, v195
	v_cmp_lt_f32_e32 vcc, s61, v113
	s_cbranch_vccz .LBB0_587
	ds_bpermute_b32 v114, v184, v113
	s_waitcnt lgkmcnt(0)
	v_max_f32_e32 v114, v114, v114
	v_max_f32_e32 v113, v113, v114
	v_max_f32_e32 v80, v113, v113
	v_max_f32_e32 v82, 0, v80
	v_exp_f32_e64 v84, -v82
	v_add_f32_e32 v161, v161, v82
	v_xor_b32_e32 v80, 0x80000000, v161
	v_pk_add_f32 v[96:97], v[96:97], v[82:83] op_sel_hi:[1,0] neg_lo:[0,1] neg_hi:[0,1]
	v_pk_add_f32 v[98:99], v[98:99], v[82:83] op_sel_hi:[1,0] neg_lo:[0,1] neg_hi:[0,1]
	v_pk_add_f32 v[100:101], v[100:101], v[82:83] op_sel_hi:[1,0] neg_lo:[0,1] neg_hi:[0,1]
	v_pk_add_f32 v[102:103], v[102:103], v[82:83] op_sel_hi:[1,0] neg_lo:[0,1] neg_hi:[0,1]
	v_pk_add_f32 v[104:105], v[104:105], v[82:83] op_sel_hi:[1,0] neg_lo:[0,1] neg_hi:[0,1]
	v_pk_add_f32 v[106:107], v[106:107], v[82:83] op_sel_hi:[1,0] neg_lo:[0,1] neg_hi:[0,1]
	v_pk_add_f32 v[108:109], v[108:109], v[82:83] op_sel_hi:[1,0] neg_lo:[0,1] neg_hi:[0,1]
	v_pk_add_f32 v[110:111], v[110:111], v[82:83] op_sel_hi:[1,0] neg_lo:[0,1] neg_hi:[0,1]
	v_pk_mul_f32 v[62:63], v[62:63], v[84:85] op_sel_hi:[1,0]
	v_pk_mul_f32 v[60:61], v[60:61], v[84:85] op_sel_hi:[1,0]
	v_pk_mul_f32 v[58:59], v[58:59], v[84:85] op_sel_hi:[1,0]
	v_pk_mul_f32 v[56:57], v[56:57], v[84:85] op_sel_hi:[1,0]
	v_pk_mul_f32 v[54:55], v[54:55], v[84:85] op_sel_hi:[1,0]
	v_pk_mul_f32 v[52:53], v[52:53], v[84:85] op_sel_hi:[1,0]
	v_pk_mul_f32 v[50:51], v[50:51], v[84:85] op_sel_hi:[1,0]
	v_pk_mul_f32 v[48:49], v[48:49], v[84:85] op_sel_hi:[1,0]
	v_pk_mul_f32 v[78:79], v[78:79], v[84:85] op_sel_hi:[1,0]
	v_pk_mul_f32 v[76:77], v[76:77], v[84:85] op_sel_hi:[1,0]
	v_pk_mul_f32 v[74:75], v[74:75], v[84:85] op_sel_hi:[1,0]
	v_pk_mul_f32 v[72:73], v[72:73], v[84:85] op_sel_hi:[1,0]
	v_pk_mul_f32 v[70:71], v[70:71], v[84:85] op_sel_hi:[1,0]
	v_pk_mul_f32 v[68:69], v[68:69], v[84:85] op_sel_hi:[1,0]
	v_pk_mul_f32 v[66:67], v[66:67], v[84:85] op_sel_hi:[1,0]
	v_pk_mul_f32 v[64:65], v[64:65], v[84:85] op_sel_hi:[1,0]
	v_mul_f32_e32 v112, v112, v84
	v_mov_b32_e32 v81, v80
	v_mov_b32_e32 v82, v80
	v_mov_b32_e32 v83, v80
	v_mov_b32_e32 v84, v80
	v_mov_b32_e32 v85, v80
	v_mov_b32_e32 v86, v80
	v_mov_b32_e32 v87, v80
	v_mov_b32_e32 v88, v80
	v_mov_b32_e32 v89, v80
	v_mov_b32_e32 v90, v80
	v_mov_b32_e32 v91, v80
	v_mov_b32_e32 v92, v80
	v_mov_b32_e32 v93, v80
	v_mov_b32_e32 v94, v80
	v_mov_b32_e32 v95, v80
.LBB0_587:
	v_exp_f32_e32 v96, v96
	v_exp_f32_e32 v97, v97
	v_exp_f32_e32 v98, v98
	v_exp_f32_e32 v99, v99
	v_exp_f32_e32 v100, v100
	v_exp_f32_e32 v101, v101
	v_exp_f32_e32 v102, v102
	v_exp_f32_e32 v103, v103
	v_cvt_pk_bf16_f32 v114, v96, v97
	v_cvt_pk_bf16_f32 v115, v98, v99
	v_cvt_pk_bf16_f32 v116, v100, v101
	v_cvt_pk_bf16_f32 v117, v102, v103
	v_exp_f32_e32 v104, v104
	v_exp_f32_e32 v105, v105
	s_waitcnt lgkmcnt(0)
	v_mfma_f32_32x32x16_bf16 v[48:63], v[220:223], v[114:117], v[48:63]
	v_exp_f32_e32 v106, v106
	v_exp_f32_e32 v107, v107
	v_exp_f32_e32 v108, v108
	v_exp_f32_e32 v109, v109
	v_exp_f32_e32 v110, v110
	v_exp_f32_e32 v111, v111
	v_cvt_pk_bf16_f32 v118, v104, v105
	v_cvt_pk_bf16_f32 v119, v106, v107
	v_cvt_pk_bf16_f32 v120, v108, v109
	v_cvt_pk_bf16_f32 v121, v110, v111
	s_andn2_b64 vcc, exec, s[14:15]
	s_waitcnt lgkmcnt(0)
	v_mfma_f32_32x32x16_bf16 v[48:63], v[224:227], v[118:121], v[48:63]
	s_waitcnt lgkmcnt(0)
	v_mfma_f32_32x32x16_bf16 v[64:79], v[236:239], v[114:117], v[64:79]
	s_waitcnt lgkmcnt(0)
	v_mfma_f32_32x32x16_bf16 v[64:79], v[200:203], v[118:121], v[64:79]
	s_cbranch_vccnz .LBB0_574
	s_xor_b32 s14, s8, 1
	s_mulk_i32 s14, 0x2400
	s_add_i32 s15, s14, 0
	v_add_u32_e32 v113, s15, v189
	s_waitcnt vmcnt(0)
	ds_write_b128 v113, v[148:151]
	s_and_saveexec_b64 s[8:9], s[36:37]
	s_cbranch_execz .LBB0_573
	v_add_u32_e32 v113, s15, v188
	ds_write_b128 v113, v[144:147]
	s_branch .LBB0_573

; __device__ __forceinline__ int otid() { int t = threadIdx.x; asm volatile("" : "+v"(t)); return t; }
; __device__ __forceinline__ unsigned cvt_pk_bf16(float lo, float hi) { typedef float f2 __attribute__((ext_vector_type(2))); typedef __bf16 b2 __attribute__((ext_vector_type(2))); f2 v = {lo, hi}; b2 b = __builtin_convertvector(v, b2); return __builtin_bit_cast(unsigned, b); }
;     __device__ __forceinline__ void operator()(f32x4 (&acc)[2][2][4][2], const Unit& u, int wr, int wc, int fr, int fq) const {
;         const int i = u.pn >> 2, pn = u.pn & 3, pm = u.pm - i * nM;
;         { const int t_ = otid(), l_ = t_ & 63, w_ = t_ >> 6; wr = w_ >> 2; wc = w_ & 3; fr = l_ & 15; fq = l_ >> 4; }
;         const int row0 = pm * BM + wr * 64 + fr; const int col0 = pn * BM + wc * 32 + 8 * fq;
;         u32x4 gwv[2][4][2];
; #pragma unroll
;         for (int ai = 0; ai < 2; ++ai)
; #pragma unroll
;             for (int m = 0; m < 4; ++m) { const bf16_t* grow = rat + ((size_t)i * Trows + (row0 + ai * HALF + m * 16)) * 1024 + col0;
; #pragma unroll
;                 for (int bj = 0; bj < 2; ++bj) gwv[ai][m][bj] = __builtin_nontemporal_load((const u32x4*)(grow + bj * HALF)); }
; #pragma unroll
;         for (int ai = 0; ai < 2; ++ai)
; #pragma unroll
;             for (int m = 0; m < 4; ++m) { bf16_t* brow = mb + (size_t)(row0 + ai * HALF + m * 16) * 1024 + col0;
; #pragma unroll
;                 for (int bj = 0; bj < 2; ++bj) { const u32x4 gw = gwv[ai][m][bj]; u32x4 w = {0u, 0u, 0u, 0u};
; #pragma unroll
;                     for (int n = 0; n < 2; ++n) { const unsigned lo = gw[2 * n], hi_ = gw[2 * n + 1];
;                         f32x4 g; g[0] = __uint_as_float(lo << 16); g[1] = __uint_as_float(lo & 0xffff0000u); g[2] = __uint_as_float(hi_ << 16); g[3] = __uint_as_float(hi_ & 0xffff0000u);
;                         const f32x4 v = acc[ai][bj][m][n] * g; acc[ai][bj][m][n] = v;
;                         if (i == 3) { w[2 * n] = cvt_pk_bf16(v[0], v[1]); w[2 * n + 1] = cvt_pk_bf16(v[2], v[3]); } }
;                     if (i == 3) *(u32x4*)(brow + bj * HALF) = w; } }
.LBB0_867:
	s_ashr_i32 s21, s60, 2
	v_mov_b32_e32 v80, v240
	s_mul_i32 s23, s21, s75
	s_sub_i32 s23, s62, s23
	v_ashrrev_i32_e32 v81, 2, v80
	v_and_b32_e32 v81, 0xffffffc0, v81
	v_lshl_add_u32 v81, s23, 8, v81
	v_and_or_b32 v216, v80, 15, v81
	s_lshl_b32 s23, s60, 8
	v_lshrrev_b32_e32 v80, 1, v80
	s_and_b32 s23, s23, 0x300
	v_and_b32_e32 v80, 0x78, v80
	v_or_b32_e32 v80, s23, v80
	v_ashrrev_i32_e32 v217, 31, v216
	v_mov_b32_e32 v132, s0
	v_lshlrev_b32_e32 v192, 1, v80
	v_mad_i64_i32 v[80:81], s[36:37], s21, v132, v[216:217]
	v_lshl_add_u64 v[128:129], s[6:7], 0, v[192:193]
	v_lshlrev_b64 v[80:81], 11, v[80:81]
	v_or_b32_e32 v214, 16, v216
	v_lshl_add_u64 v[80:81], v[128:129], 0, v[80:81]
	v_ashrrev_i32_e32 v215, 31, v214
	global_load_dwordx4 v[188:191], v[80:81], off nt
	global_load_dwordx4 v[184:187], v[80:81], off offset:256 nt
	v_mad_i64_i32 v[80:81], s[36:37], s21, v132, v[214:215]
	v_lshlrev_b64 v[80:81], 11, v[80:81]
	v_or_b32_e32 v212, 32, v216
	v_lshl_add_u64 v[80:81], v[128:129], 0, v[80:81]
	v_ashrrev_i32_e32 v213, 31, v212
	global_load_dwordx4 v[180:183], v[80:81], off nt
	global_load_dwordx4 v[176:179], v[80:81], off offset:256 nt
	v_mad_i64_i32 v[80:81], s[36:37], s21, v132, v[212:213]
	v_lshlrev_b64 v[80:81], 11, v[80:81]
	v_or_b32_e32 v210, 48, v216
	v_lshl_add_u64 v[80:81], v[128:129], 0, v[80:81]
	v_ashrrev_i32_e32 v211, 31, v210
	global_load_dwordx4 v[172:175], v[80:81], off nt
	global_load_dwordx4 v[168:171], v[80:81], off offset:256 nt
	v_mad_i64_i32 v[80:81], s[36:37], s21, v132, v[210:211]
	v_lshlrev_b64 v[80:81], 11, v[80:81]
	v_add_u32_e32 v208, 0x80, v216
	v_lshl_add_u64 v[130:131], v[128:129], 0, v[80:81]
	v_ashrrev_i32_e32 v209, 31, v208
	global_load_dwordx4 v[80:83], v[130:131], off nt
	global_load_dwordx4 v[164:167], v[130:131], off offset:256 nt
	v_mad_i64_i32 v[130:131], s[36:37], s21, v132, v[208:209]
	v_lshlrev_b64 v[130:131], 11, v[130:131]
	v_add_u32_e32 v206, 0x90, v216
	v_lshl_add_u64 v[130:131], v[128:129], 0, v[130:131]
	v_ashrrev_i32_e32 v207, 31, v206
	global_load_dwordx4 v[160:163], v[130:131], off nt
	global_load_dwordx4 v[156:159], v[130:131], off offset:256 nt
	v_mad_i64_i32 v[130:131], s[36:37], s21, v132, v[206:207]
	v_lshlrev_b64 v[130:131], 11, v[130:131]
	v_add_u32_e32 v204, 0xa0, v216
	v_lshl_add_u64 v[130:131], v[128:129], 0, v[130:131]
	v_ashrrev_i32_e32 v205, 31, v204
	global_load_dwordx4 v[148:151], v[130:131], off nt
	global_load_dwordx4 v[144:147], v[130:131], off offset:256 nt
	v_mad_i64_i32 v[130:131], s[36:37], s21, v132, v[204:205]
	v_lshlrev_b64 v[130:131], 11, v[130:131]
	v_add_u32_e32 v202, 0xb0, v216
	v_lshl_add_u64 v[130:131], v[128:129], 0, v[130:131]
	v_ashrrev_i32_e32 v203, 31, v202
	global_load_dwordx4 v[140:143], v[130:131], off nt
	global_load_dwordx4 v[136:139], v[130:131], off offset:256 nt
	v_mad_i64_i32 v[130:131], s[36:37], s21, v132, v[202:203]
	v_lshlrev_b64 v[130:131], 11, v[130:131]
	v_lshl_add_u64 v[128:129], v[128:129], 0, v[130:131]
	global_load_dwordx4 v[132:135], v[128:129], off nt
	s_nop 0
	global_load_dwordx4 v[128:131], v[128:129], off offset:256 nt
	s_cmp_eq_u32 s21, 3
	s_cselect_b64 s[40:41], -1, 0
	s_cmp_lg_u32 s21, 3
	s_waitcnt vmcnt(15) lgkmcnt(0)
	v_lshlrev_b32_e32 v220, 16, v188
	v_and_b32_e32 v221, 0xffff0000, v188
	v_lshlrev_b32_e32 v188, 16, v189
	v_and_b32_e32 v189, 0xffff0000, v189
	v_pk_mul_f32 v[2:3], v[2:3], v[188:189]
	v_pk_mul_f32 v[0:1], v[0:1], v[220:221]
	v_mov_b32_e32 v188, 0
	v_mov_b32_e32 v189, 0
	s_cbranch_scc1 .LBB0_869
	v_cvt_pk_bf16_f32 v188, v0, v1
	v_cvt_pk_bf16_f32 v189, v2, v3

; __device__ __forceinline__ unsigned cvt_pk_bf16(float lo, float hi) { typedef float f2 __attribute__((ext_vector_type(2))); typedef __bf16 b2 __attribute__((ext_vector_type(2))); f2 v = {lo, hi}; b2 b = __builtin_convertvector(v, b2); return __builtin_bit_cast(unsigned, b); }
;     __device__ __forceinline__ void operator()(f32x4 (&acc)[2][2][4][2], const Unit& u, int wr, int wc, int fr, int fq) const {
;     ...
;                 for (int bj = 0; bj < 2; ++bj) { const u32x4 gw = gwv[ai][m][bj]; u32x4 w = {0u, 0u, 0u, 0u};
; #pragma unroll
;                     for (int n = 0; n < 2; ++n) { const unsigned lo = gw[2 * n], hi_ = gw[2 * n + 1];
;                         f32x4 g; g[0] = __uint_as_float(lo << 16); g[1] = __uint_as_float(lo & 0xffff0000u); g[2] = __uint_as_float(hi_ << 16); g[3] = __uint_as_float(hi_ & 0xffff0000u);
;                         const f32x4 v = acc[ai][bj][m][n] * g; acc[ai][bj][m][n] = v;
;                         if (i == 3) { w[2 * n] = cvt_pk_bf16(v[0], v[1]); w[2 * n + 1] = cvt_pk_bf16(v[2], v[3]); } }
.LBB0_871:
	s_nop 1
	s_waitcnt vmcnt(14)
	v_lshlrev_b32_e32 v188, 16, v184
	v_and_b32_e32 v189, 0xffff0000, v184
	v_lshlrev_b32_e32 v184, 16, v185
	v_and_b32_e32 v185, 0xffff0000, v185
	v_pk_mul_f32 v[6:7], v[6:7], v[184:185]
	v_pk_mul_f32 v[4:5], v[4:5], v[188:189]
	v_mov_b32_e32 v184, 0
	s_and_b64 vcc, exec, s[36:37]
	v_mov_b32_e32 v185, 0
	s_cbranch_vccnz .LBB0_873
	v_cvt_pk_bf16_f32 v184, v4, v5
	v_cvt_pk_bf16_f32 v185, v6, v7

; __device__ __forceinline__ unsigned cvt_pk_bf16(float lo, float hi) { typedef float f2 __attribute__((ext_vector_type(2))); typedef __bf16 b2 __attribute__((ext_vector_type(2))); f2 v = {lo, hi}; b2 b = __builtin_convertvector(v, b2); return __builtin_bit_cast(unsigned, b); }
;     __device__ __forceinline__ void operator()(f32x4 (&acc)[2][2][4][2], const Unit& u, int wr, int wc, int fr, int fq) const {
;     ...
;                 for (int bj = 0; bj < 2; ++bj) { const u32x4 gw = gwv[ai][m][bj]; u32x4 w = {0u, 0u, 0u, 0u};
; #pragma unroll
;                     for (int n = 0; n < 2; ++n) { const unsigned lo = gw[2 * n], hi_ = gw[2 * n + 1];
;                         f32x4 g; g[0] = __uint_as_float(lo << 16); g[1] = __uint_as_float(lo & 0xffff0000u); g[2] = __uint_as_float(hi_ << 16); g[3] = __uint_as_float(hi_ & 0xffff0000u);
;                         const f32x4 v = acc[ai][bj][m][n] * g; acc[ai][bj][m][n] = v;
;                         if (i == 3) { w[2 * n] = cvt_pk_bf16(v[0], v[1]); w[2 * n + 1] = cvt_pk_bf16(v[2], v[3]); } }
.LBB0_875:
	s_nop 1
	s_waitcnt vmcnt(13)
	v_lshlrev_b32_e32 v184, 16, v180
	v_and_b32_e32 v185, 0xffff0000, v180
	v_lshlrev_b32_e32 v180, 16, v181
	v_and_b32_e32 v181, 0xffff0000, v181
	v_pk_mul_f32 v[26:27], v[26:27], v[180:181]
	v_pk_mul_f32 v[24:25], v[24:25], v[184:185]
	v_mov_b32_e32 v180, 0
	s_and_b64 vcc, exec, s[36:37]
	v_mov_b32_e32 v181, 0
	s_cbranch_vccnz .LBB0_877
	v_cvt_pk_bf16_f32 v180, v24, v25
	v_cvt_pk_bf16_f32 v181, v26, v27

; __device__ __forceinline__ unsigned cvt_pk_bf16(float lo, float hi) { typedef float f2 __attribute__((ext_vector_type(2))); typedef __bf16 b2 __attribute__((ext_vector_type(2))); f2 v = {lo, hi}; b2 b = __builtin_convertvector(v, b2); return __builtin_bit_cast(unsigned, b); }
;     __device__ __forceinline__ void operator()(f32x4 (&acc)[2][2][4][2], const Unit& u, int wr, int wc, int fr, int fq) const {
;     ...
;                 for (int bj = 0; bj < 2; ++bj) { const u32x4 gw = gwv[ai][m][bj]; u32x4 w = {0u, 0u, 0u, 0u};
; #pragma unroll
;                     for (int n = 0; n < 2; ++n) { const unsigned lo = gw[2 * n], hi_ = gw[2 * n + 1];
;                         f32x4 g; g[0] = __uint_as_float(lo << 16); g[1] = __uint_as_float(lo & 0xffff0000u); g[2] = __uint_as_float(hi_ << 16); g[3] = __uint_as_float(hi_ & 0xffff0000u);
;                         const f32x4 v = acc[ai][bj][m][n] * g; acc[ai][bj][m][n] = v;
;                         if (i == 3) { w[2 * n] = cvt_pk_bf16(v[0], v[1]); w[2 * n + 1] = cvt_pk_bf16(v[2], v[3]); } }
.LBB0_879:
	s_nop 1
	s_waitcnt vmcnt(12)
	v_lshlrev_b32_e32 v180, 16, v176
	v_and_b32_e32 v181, 0xffff0000, v176
	v_lshlrev_b32_e32 v176, 16, v177
	v_and_b32_e32 v177, 0xffff0000, v177
	v_pk_mul_f32 v[18:19], v[18:19], v[176:177]
	v_pk_mul_f32 v[16:17], v[16:17], v[180:181]
	v_mov_b32_e32 v176, 0
	s_and_b64 vcc, exec, s[36:37]
	v_mov_b32_e32 v177, 0
	s_cbranch_vccnz .LBB0_881
	v_cvt_pk_bf16_f32 v176, v16, v17
	v_cvt_pk_bf16_f32 v177, v18, v19

; __device__ __forceinline__ unsigned cvt_pk_bf16(float lo, float hi) { typedef float f2 __attribute__((ext_vector_type(2))); typedef __bf16 b2 __attribute__((ext_vector_type(2))); f2 v = {lo, hi}; b2 b = __builtin_convertvector(v, b2); return __builtin_bit_cast(unsigned, b); }
;     __device__ __forceinline__ void operator()(f32x4 (&acc)[2][2][4][2], const Unit& u, int wr, int wc, int fr, int fq) const {
;     ...
;                 for (int bj = 0; bj < 2; ++bj) { const u32x4 gw = gwv[ai][m][bj]; u32x4 w = {0u, 0u, 0u, 0u};
; #pragma unroll
;                     for (int n = 0; n < 2; ++n) { const unsigned lo = gw[2 * n], hi_ = gw[2 * n + 1];
;                         f32x4 g; g[0] = __uint_as_float(lo << 16); g[1] = __uint_as_float(lo & 0xffff0000u); g[2] = __uint_as_float(hi_ << 16); g[3] = __uint_as_float(hi_ & 0xffff0000u);
;                         const f32x4 v = acc[ai][bj][m][n] * g; acc[ai][bj][m][n] = v;
;                         if (i == 3) { w[2 * n] = cvt_pk_bf16(v[0], v[1]); w[2 * n + 1] = cvt_pk_bf16(v[2], v[3]); } }
.LBB0_883:
	s_nop 1
	s_waitcnt vmcnt(11)
	v_lshlrev_b32_e32 v176, 16, v172
	v_and_b32_e32 v177, 0xffff0000, v172
	v_lshlrev_b32_e32 v172, 16, v173
	v_and_b32_e32 v173, 0xffff0000, v173
	v_pk_mul_f32 v[42:43], v[42:43], v[172:173]
	v_pk_mul_f32 v[40:41], v[40:41], v[176:177]
	v_mov_b32_e32 v172, 0
	s_and_b64 vcc, exec, s[36:37]
	v_mov_b32_e32 v173, 0
	s_cbranch_vccnz .LBB0_885
	v_cvt_pk_bf16_f32 v172, v40, v41
	v_cvt_pk_bf16_f32 v173, v42, v43

; __device__ __forceinline__ unsigned cvt_pk_bf16(float lo, float hi) { typedef float f2 __attribute__((ext_vector_type(2))); typedef __bf16 b2 __attribute__((ext_vector_type(2))); f2 v = {lo, hi}; b2 b = __builtin_convertvector(v, b2); return __builtin_bit_cast(unsigned, b); }
;     __device__ __forceinline__ void operator()(f32x4 (&acc)[2][2][4][2], const Unit& u, int wr, int wc, int fr, int fq) const {
;     ...
;                 for (int bj = 0; bj < 2; ++bj) { const u32x4 gw = gwv[ai][m][bj]; u32x4 w = {0u, 0u, 0u, 0u};
; #pragma unroll
;                     for (int n = 0; n < 2; ++n) { const unsigned lo = gw[2 * n], hi_ = gw[2 * n + 1];
;                         f32x4 g; g[0] = __uint_as_float(lo << 16); g[1] = __uint_as_float(lo & 0xffff0000u); g[2] = __uint_as_float(hi_ << 16); g[3] = __uint_as_float(hi_ & 0xffff0000u);
;                         const f32x4 v = acc[ai][bj][m][n] * g; acc[ai][bj][m][n] = v;
;                         if (i == 3) { w[2 * n] = cvt_pk_bf16(v[0], v[1]); w[2 * n + 1] = cvt_pk_bf16(v[2], v[3]); } }
.LBB0_887:
	s_nop 1
	s_waitcnt vmcnt(10)
	v_lshlrev_b32_e32 v172, 16, v168
	v_and_b32_e32 v173, 0xffff0000, v168
	v_lshlrev_b32_e32 v168, 16, v169
	v_and_b32_e32 v169, 0xffff0000, v169
	v_pk_mul_f32 v[34:35], v[34:35], v[168:169]
	v_pk_mul_f32 v[32:33], v[32:33], v[172:173]
	v_mov_b32_e32 v168, 0
	s_and_b64 vcc, exec, s[36:37]
	v_mov_b32_e32 v169, 0
	s_cbranch_vccnz .LBB0_889
	v_cvt_pk_bf16_f32 v168, v32, v33
	v_cvt_pk_bf16_f32 v169, v34, v35

; __device__ __forceinline__ unsigned cvt_pk_bf16(float lo, float hi) { typedef float f2 __attribute__((ext_vector_type(2))); typedef __bf16 b2 __attribute__((ext_vector_type(2))); f2 v = {lo, hi}; b2 b = __builtin_convertvector(v, b2); return __builtin_bit_cast(unsigned, b); }
;     __device__ __forceinline__ void operator()(f32x4 (&acc)[2][2][4][2], const Unit& u, int wr, int wc, int fr, int fq) const {
;     ...
;                 for (int bj = 0; bj < 2; ++bj) { const u32x4 gw = gwv[ai][m][bj]; u32x4 w = {0u, 0u, 0u, 0u};
; #pragma unroll
;                     for (int n = 0; n < 2; ++n) { const unsigned lo = gw[2 * n], hi_ = gw[2 * n + 1];
;                         f32x4 g; g[0] = __uint_as_float(lo << 16); g[1] = __uint_as_float(lo & 0xffff0000u); g[2] = __uint_as_float(hi_ << 16); g[3] = __uint_as_float(hi_ & 0xffff0000u);
;                         const f32x4 v = acc[ai][bj][m][n] * g; acc[ai][bj][m][n] = v;
;                         if (i == 3) { w[2 * n] = cvt_pk_bf16(v[0], v[1]); w[2 * n + 1] = cvt_pk_bf16(v[2], v[3]); } }
.LBB0_891:
	s_nop 1
	s_waitcnt vmcnt(9)
	v_lshlrev_b32_e32 v168, 16, v80
	v_and_b32_e32 v169, 0xffff0000, v80
	v_lshlrev_b32_e32 v80, 16, v81
	v_and_b32_e32 v81, 0xffff0000, v81
	v_pk_mul_f32 v[74:75], v[74:75], v[80:81]
	v_pk_mul_f32 v[72:73], v[72:73], v[168:169]
	v_mov_b32_e32 v168, 0
	s_and_b64 vcc, exec, s[36:37]
	v_mov_b32_e32 v169, 0
	s_cbranch_vccnz .LBB0_893
	v_cvt_pk_bf16_f32 v168, v72, v73
	v_cvt_pk_bf16_f32 v169, v74, v75

; __device__ __forceinline__ unsigned cvt_pk_bf16(float lo, float hi) { typedef float f2 __attribute__((ext_vector_type(2))); typedef __bf16 b2 __attribute__((ext_vector_type(2))); f2 v = {lo, hi}; b2 b = __builtin_convertvector(v, b2); return __builtin_bit_cast(unsigned, b); }
;     __device__ __forceinline__ void operator()(f32x4 (&acc)[2][2][4][2], const Unit& u, int wr, int wc, int fr, int fq) const {
;     ...
;                 for (int bj = 0; bj < 2; ++bj) { const u32x4 gw = gwv[ai][m][bj]; u32x4 w = {0u, 0u, 0u, 0u};
; #pragma unroll
;                     for (int n = 0; n < 2; ++n) { const unsigned lo = gw[2 * n], hi_ = gw[2 * n + 1];
;                         f32x4 g; g[0] = __uint_as_float(lo << 16); g[1] = __uint_as_float(lo & 0xffff0000u); g[2] = __uint_as_float(hi_ << 16); g[3] = __uint_as_float(hi_ & 0xffff0000u);
;                         const f32x4 v = acc[ai][bj][m][n] * g; acc[ai][bj][m][n] = v;
;                         if (i == 3) { w[2 * n] = cvt_pk_bf16(v[0], v[1]); w[2 * n + 1] = cvt_pk_bf16(v[2], v[3]); } }
.LBB0_895:
	s_waitcnt vmcnt(8)
	v_lshlrev_b32_e32 v68, 16, v164
	v_and_b32_e32 v69, 0xffff0000, v164
	v_lshlrev_b32_e32 v70, 16, v165
	v_and_b32_e32 v71, 0xffff0000, v165
	v_pk_mul_f32 v[62:63], v[62:63], v[70:71]
	v_pk_mul_f32 v[60:61], v[60:61], v[68:69]
	v_mov_b32_e32 v164, 0
	s_and_b64 vcc, exec, s[36:37]
	v_mov_b32_e32 v165, 0
	s_cbranch_vccnz .LBB0_897
	v_cvt_pk_bf16_f32 v164, v60, v61
	v_cvt_pk_bf16_f32 v165, v62, v63

; __device__ __forceinline__ unsigned cvt_pk_bf16(float lo, float hi) { typedef float f2 __attribute__((ext_vector_type(2))); typedef __bf16 b2 __attribute__((ext_vector_type(2))); f2 v = {lo, hi}; b2 b = __builtin_convertvector(v, b2); return __builtin_bit_cast(unsigned, b); }
;     __device__ __forceinline__ void operator()(f32x4 (&acc)[2][2][4][2], const Unit& u, int wr, int wc, int fr, int fq) const {
;     ...
;                 for (int bj = 0; bj < 2; ++bj) { const u32x4 gw = gwv[ai][m][bj]; u32x4 w = {0u, 0u, 0u, 0u};
; #pragma unroll
;                     for (int n = 0; n < 2; ++n) { const unsigned lo = gw[2 * n], hi_ = gw[2 * n + 1];
;                         f32x4 g; g[0] = __uint_as_float(lo << 16); g[1] = __uint_as_float(lo & 0xffff0000u); g[2] = __uint_as_float(hi_ << 16); g[3] = __uint_as_float(hi_ & 0xffff0000u);
;                         const f32x4 v = acc[ai][bj][m][n] * g; acc[ai][bj][m][n] = v;
;                         if (i == 3) { w[2 * n] = cvt_pk_bf16(v[0], v[1]); w[2 * n + 1] = cvt_pk_bf16(v[2], v[3]); } }
.LBB0_899:
	s_waitcnt vmcnt(7)
	v_lshlrev_b32_e32 v56, 16, v160
	v_and_b32_e32 v57, 0xffff0000, v160
	v_lshlrev_b32_e32 v58, 16, v161
	v_and_b32_e32 v59, 0xffff0000, v161
	v_pk_mul_f32 v[58:59], v[154:155], v[58:59]
	v_pk_mul_f32 v[56:57], v[152:153], v[56:57]
	v_mov_b32_e32 v152, 0
	s_and_b64 vcc, exec, s[36:37]
	v_mov_b32_e32 v153, 0
	s_cbranch_vccnz .LBB0_901
	v_cvt_pk_bf16_f32 v152, v56, v57
	v_cvt_pk_bf16_f32 v153, v58, v59

; __device__ __forceinline__ unsigned cvt_pk_bf16(float lo, float hi) { typedef float f2 __attribute__((ext_vector_type(2))); typedef __bf16 b2 __attribute__((ext_vector_type(2))); f2 v = {lo, hi}; b2 b = __builtin_convertvector(v, b2); return __builtin_bit_cast(unsigned, b); }
;     __device__ __forceinline__ void operator()(f32x4 (&acc)[2][2][4][2], const Unit& u, int wr, int wc, int fr, int fq) const {
;     ...
;                 for (int bj = 0; bj < 2; ++bj) { const u32x4 gw = gwv[ai][m][bj]; u32x4 w = {0u, 0u, 0u, 0u};
; #pragma unroll
;                     for (int n = 0; n < 2; ++n) { const unsigned lo = gw[2 * n], hi_ = gw[2 * n + 1];
;                         f32x4 g; g[0] = __uint_as_float(lo << 16); g[1] = __uint_as_float(lo & 0xffff0000u); g[2] = __uint_as_float(hi_ << 16); g[3] = __uint_as_float(hi_ & 0xffff0000u);
;                         const f32x4 v = acc[ai][bj][m][n] * g; acc[ai][bj][m][n] = v;
;                         if (i == 3) { w[2 * n] = cvt_pk_bf16(v[0], v[1]); w[2 * n + 1] = cvt_pk_bf16(v[2], v[3]); } }
.LBB0_903:
	s_nop 1
	s_waitcnt vmcnt(6)
	v_lshlrev_b32_e32 v152, 16, v156
	v_and_b32_e32 v153, 0xffff0000, v156
	v_lshlrev_b32_e32 v154, 16, v157
	v_and_b32_e32 v155, 0xffff0000, v157
	v_pk_mul_f32 v[46:47], v[46:47], v[154:155]
	v_pk_mul_f32 v[44:45], v[44:45], v[152:153]
	v_mov_b32_e32 v152, 0
	s_and_b64 vcc, exec, s[36:37]
	v_mov_b32_e32 v153, 0
	s_cbranch_vccnz .LBB0_905
	v_cvt_pk_bf16_f32 v152, v44, v45
	v_cvt_pk_bf16_f32 v153, v46, v47

; __device__ __forceinline__ unsigned cvt_pk_bf16(float lo, float hi) { typedef float f2 __attribute__((ext_vector_type(2))); typedef __bf16 b2 __attribute__((ext_vector_type(2))); f2 v = {lo, hi}; b2 b = __builtin_convertvector(v, b2); return __builtin_bit_cast(unsigned, b); }
;     __device__ __forceinline__ void operator()(f32x4 (&acc)[2][2][4][2], const Unit& u, int wr, int wc, int fr, int fq) const {
;     ...
;                 for (int bj = 0; bj < 2; ++bj) { const u32x4 gw = gwv[ai][m][bj]; u32x4 w = {0u, 0u, 0u, 0u};
; #pragma unroll
;                     for (int n = 0; n < 2; ++n) { const unsigned lo = gw[2 * n], hi_ = gw[2 * n + 1];
;                         f32x4 g; g[0] = __uint_as_float(lo << 16); g[1] = __uint_as_float(lo & 0xffff0000u); g[2] = __uint_as_float(hi_ << 16); g[3] = __uint_as_float(hi_ & 0xffff0000u);
;                         const f32x4 v = acc[ai][bj][m][n] * g; acc[ai][bj][m][n] = v;
;                         if (i == 3) { w[2 * n] = cvt_pk_bf16(v[0], v[1]); w[2 * n + 1] = cvt_pk_bf16(v[2], v[3]); } }
.LBB0_907:
	s_nop 1
	s_waitcnt vmcnt(5)
	v_lshlrev_b32_e32 v152, 16, v148
	v_and_b32_e32 v153, 0xffff0000, v148
	v_lshlrev_b32_e32 v148, 16, v149
	v_and_b32_e32 v149, 0xffff0000, v149
	v_pk_mul_f32 v[90:91], v[90:91], v[148:149]
	v_pk_mul_f32 v[88:89], v[88:89], v[152:153]
	v_mov_b32_e32 v148, 0
	s_and_b64 vcc, exec, s[36:37]
	v_mov_b32_e32 v149, 0
	s_cbranch_vccnz .LBB0_909
	v_cvt_pk_bf16_f32 v148, v88, v89
	v_cvt_pk_bf16_f32 v149, v90, v91

; __device__ __forceinline__ unsigned cvt_pk_bf16(float lo, float hi) { typedef float f2 __attribute__((ext_vector_type(2))); typedef __bf16 b2 __attribute__((ext_vector_type(2))); f2 v = {lo, hi}; b2 b = __builtin_convertvector(v, b2); return __builtin_bit_cast(unsigned, b); }
;     __device__ __forceinline__ void operator()(f32x4 (&acc)[2][2][4][2], const Unit& u, int wr, int wc, int fr, int fq) const {
;     ...
;                 for (int bj = 0; bj < 2; ++bj) { const u32x4 gw = gwv[ai][m][bj]; u32x4 w = {0u, 0u, 0u, 0u};
; #pragma unroll
;                     for (int n = 0; n < 2; ++n) { const unsigned lo = gw[2 * n], hi_ = gw[2 * n + 1];
;                         f32x4 g; g[0] = __uint_as_float(lo << 16); g[1] = __uint_as_float(lo & 0xffff0000u); g[2] = __uint_as_float(hi_ << 16); g[3] = __uint_as_float(hi_ & 0xffff0000u);
;                         const f32x4 v = acc[ai][bj][m][n] * g; acc[ai][bj][m][n] = v;
;                         if (i == 3) { w[2 * n] = cvt_pk_bf16(v[0], v[1]); w[2 * n + 1] = cvt_pk_bf16(v[2], v[3]); } }
.LBB0_911:
	s_nop 1
	s_waitcnt vmcnt(4)
	v_lshlrev_b32_e32 v148, 16, v144
	v_and_b32_e32 v149, 0xffff0000, v144
	v_lshlrev_b32_e32 v144, 16, v145
	v_and_b32_e32 v145, 0xffff0000, v145
	v_pk_mul_f32 v[78:79], v[78:79], v[144:145]
	v_pk_mul_f32 v[76:77], v[76:77], v[148:149]
	v_mov_b32_e32 v144, 0
	s_and_b64 vcc, exec, s[36:37]
	v_mov_b32_e32 v145, 0
	s_cbranch_vccnz .LBB0_913
	v_cvt_pk_bf16_f32 v144, v76, v77
	v_cvt_pk_bf16_f32 v145, v78, v79

; __device__ __forceinline__ unsigned cvt_pk_bf16(float lo, float hi) { typedef float f2 __attribute__((ext_vector_type(2))); typedef __bf16 b2 __attribute__((ext_vector_type(2))); f2 v = {lo, hi}; b2 b = __builtin_convertvector(v, b2); return __builtin_bit_cast(unsigned, b); }
;     __device__ __forceinline__ void operator()(f32x4 (&acc)[2][2][4][2], const Unit& u, int wr, int wc, int fr, int fq) const {
;     ...
;                 for (int bj = 0; bj < 2; ++bj) { const u32x4 gw = gwv[ai][m][bj]; u32x4 w = {0u, 0u, 0u, 0u};
; #pragma unroll
;                     for (int n = 0; n < 2; ++n) { const unsigned lo = gw[2 * n], hi_ = gw[2 * n + 1];
;                         f32x4 g; g[0] = __uint_as_float(lo << 16); g[1] = __uint_as_float(lo & 0xffff0000u); g[2] = __uint_as_float(hi_ << 16); g[3] = __uint_as_float(hi_ & 0xffff0000u);
;                         const f32x4 v = acc[ai][bj][m][n] * g; acc[ai][bj][m][n] = v;
;                         if (i == 3) { w[2 * n] = cvt_pk_bf16(v[0], v[1]); w[2 * n + 1] = cvt_pk_bf16(v[2], v[3]); } }
.LBB0_915:
	s_nop 1
	s_waitcnt vmcnt(3)
	v_lshlrev_b32_e32 v144, 16, v140
	v_and_b32_e32 v145, 0xffff0000, v140
	v_lshlrev_b32_e32 v140, 16, v141
	v_and_b32_e32 v141, 0xffff0000, v141
	v_pk_mul_f32 v[106:107], v[106:107], v[140:141]
	v_pk_mul_f32 v[104:105], v[104:105], v[144:145]
	v_mov_b32_e32 v140, 0
	s_and_b64 vcc, exec, s[36:37]
	v_mov_b32_e32 v141, 0
	s_cbranch_vccnz .LBB0_917
	v_cvt_pk_bf16_f32 v140, v104, v105
	v_cvt_pk_bf16_f32 v141, v106, v107

; __device__ __forceinline__ unsigned cvt_pk_bf16(float lo, float hi) { typedef float f2 __attribute__((ext_vector_type(2))); typedef __bf16 b2 __attribute__((ext_vector_type(2))); f2 v = {lo, hi}; b2 b = __builtin_convertvector(v, b2); return __builtin_bit_cast(unsigned, b); }
;     __device__ __forceinline__ void operator()(f32x4 (&acc)[2][2][4][2], const Unit& u, int wr, int wc, int fr, int fq) const {
;     ...
;                 for (int bj = 0; bj < 2; ++bj) { const u32x4 gw = gwv[ai][m][bj]; u32x4 w = {0u, 0u, 0u, 0u};
; #pragma unroll
;                     for (int n = 0; n < 2; ++n) { const unsigned lo = gw[2 * n], hi_ = gw[2 * n + 1];
;                         f32x4 g; g[0] = __uint_as_float(lo << 16); g[1] = __uint_as_float(lo & 0xffff0000u); g[2] = __uint_as_float(hi_ << 16); g[3] = __uint_as_float(hi_ & 0xffff0000u);
;                         const f32x4 v = acc[ai][bj][m][n] * g; acc[ai][bj][m][n] = v;
;                         if (i == 3) { w[2 * n] = cvt_pk_bf16(v[0], v[1]); w[2 * n + 1] = cvt_pk_bf16(v[2], v[3]); } }
.LBB0_919:
	s_nop 1
	s_waitcnt vmcnt(2)
	v_lshlrev_b32_e32 v140, 16, v136
	v_and_b32_e32 v141, 0xffff0000, v136
	v_lshlrev_b32_e32 v136, 16, v137
	v_and_b32_e32 v137, 0xffff0000, v137
	v_pk_mul_f32 v[98:99], v[98:99], v[136:137]
	v_pk_mul_f32 v[96:97], v[96:97], v[140:141]
	v_mov_b32_e32 v136, 0
	s_and_b64 vcc, exec, s[36:37]
	v_mov_b32_e32 v137, 0
	s_cbranch_vccnz .LBB0_921
	v_cvt_pk_bf16_f32 v136, v96, v97
	v_cvt_pk_bf16_f32 v137, v98, v99

; __device__ __forceinline__ unsigned cvt_pk_bf16(float lo, float hi) { typedef float f2 __attribute__((ext_vector_type(2))); typedef __bf16 b2 __attribute__((ext_vector_type(2))); f2 v = {lo, hi}; b2 b = __builtin_convertvector(v, b2); return __builtin_bit_cast(unsigned, b); }
;     __device__ __forceinline__ void operator()(f32x4 (&acc)[2][2][4][2], const Unit& u, int wr, int wc, int fr, int fq) const {
;     ...
;                 for (int bj = 0; bj < 2; ++bj) { const u32x4 gw = gwv[ai][m][bj]; u32x4 w = {0u, 0u, 0u, 0u};
; #pragma unroll
;                     for (int n = 0; n < 2; ++n) { const unsigned lo = gw[2 * n], hi_ = gw[2 * n + 1];
;                         f32x4 g; g[0] = __uint_as_float(lo << 16); g[1] = __uint_as_float(lo & 0xffff0000u); g[2] = __uint_as_float(hi_ << 16); g[3] = __uint_as_float(hi_ & 0xffff0000u);
;                         const f32x4 v = acc[ai][bj][m][n] * g; acc[ai][bj][m][n] = v;
;                         if (i == 3) { w[2 * n] = cvt_pk_bf16(v[0], v[1]); w[2 * n + 1] = cvt_pk_bf16(v[2], v[3]); } }
.LBB0_923:
	s_nop 1
	s_waitcnt vmcnt(1)
	v_lshlrev_b32_e32 v136, 16, v132
	v_and_b32_e32 v137, 0xffff0000, v132
	v_lshlrev_b32_e32 v132, 16, v133
	v_and_b32_e32 v133, 0xffff0000, v133
	v_pk_mul_f32 v[122:123], v[122:123], v[132:133]
	v_pk_mul_f32 v[120:121], v[120:121], v[136:137]
	v_mov_b32_e32 v132, 0
	s_and_b64 vcc, exec, s[36:37]
	v_mov_b32_e32 v133, 0
	s_cbranch_vccnz .LBB0_925
	v_cvt_pk_bf16_f32 v132, v120, v121
	v_cvt_pk_bf16_f32 v133, v122, v123

; __device__ __forceinline__ unsigned cvt_pk_bf16(float lo, float hi) { typedef float f2 __attribute__((ext_vector_type(2))); typedef __bf16 b2 __attribute__((ext_vector_type(2))); f2 v = {lo, hi}; b2 b = __builtin_convertvector(v, b2); return __builtin_bit_cast(unsigned, b); }
;     __device__ __forceinline__ void operator()(f32x4 (&acc)[2][2][4][2], const Unit& u, int wr, int wc, int fr, int fq) const {
;     ...
;                 for (int bj = 0; bj < 2; ++bj) { const u32x4 gw = gwv[ai][m][bj]; u32x4 w = {0u, 0u, 0u, 0u};
; #pragma unroll
;                     for (int n = 0; n < 2; ++n) { const unsigned lo = gw[2 * n], hi_ = gw[2 * n + 1];
;                         f32x4 g; g[0] = __uint_as_float(lo << 16); g[1] = __uint_as_float(lo & 0xffff0000u); g[2] = __uint_as_float(hi_ << 16); g[3] = __uint_as_float(hi_ & 0xffff0000u);
;                         const f32x4 v = acc[ai][bj][m][n] * g; acc[ai][bj][m][n] = v;
;                         if (i == 3) { w[2 * n] = cvt_pk_bf16(v[0], v[1]); w[2 * n + 1] = cvt_pk_bf16(v[2], v[3]); } }
.LBB0_927:
	s_nop 1
	s_waitcnt vmcnt(0)
	v_lshlrev_b32_e32 v132, 16, v128
	v_and_b32_e32 v133, 0xffff0000, v128
	v_lshlrev_b32_e32 v128, 16, v129
	v_and_b32_e32 v129, 0xffff0000, v129
	v_pk_mul_f32 v[114:115], v[114:115], v[128:129]
	v_pk_mul_f32 v[112:113], v[112:113], v[132:133]
	v_mov_b32_e32 v128, 0
	s_and_b64 vcc, exec, s[36:37]
	v_mov_b32_e32 v129, 0
	s_cbranch_vccnz .LBB0_929
	v_cvt_pk_bf16_f32 v128, v112, v113
	v_cvt_pk_bf16_f32 v129, v114, v115
